# MFMA-shadow fill: the B1 fragment LDS reads of phases 2/6 are issued by the wave inside its own preceding MFMA segment
# baseline (speedup 1.0000x reference)
.Lg131_noy:
	ds_read_b128 v[152:155], v149
	ds_read_b128 v[156:159], v149 offset:1024
	ds_read_b128 v[160:163], v149 offset:2048
	ds_read_b128 v[164:167], v149 offset:3072
	s_add_u32 s26, s20, 0xfffc0080
	s_addc_u32 s27, s21, -1
	s_cmp_eq_u32 s57, 12
	s_cselect_b32 s29, s13, s27
	s_cselect_b32 s28, s53, s26
	s_cselect_b32 s27, s11, s56
	s_cselect_b32 s26, s54, s55
	s_add_i32 m0, s19, 0xc000
	ds_read_b128 v[168:171], v150
	ds_read_b128 v[172:175], v150 offset:1024
	ds_read_b128 v[176:179], v150 offset:2048
	ds_read_b128 v[180:183], v150 offset:3072
	ds_read_b128 v[184:187], v150 offset:4096
	ds_read_b128 v[188:191], v150 offset:5120
	ds_read_b128 v[192:195], v150 offset:6144
	ds_read_b128 v[196:199], v150 offset:7168
	global_load_lds_dwordx4 v136, s[20:21]
	s_add_i32 m0, s19, 0xe000
	s_nop 0
	global_load_lds_dwordx4 v138, s[20:21]
	s_waitcnt lgkmcnt(8)
	s_barrier
	s_waitcnt lgkmcnt(0)
	s_waitcnt lgkmcnt(0)
	v_mfma_f32_16x16x32_bf16 v[124:127], v[152:155], v[168:171], 0
	ds_read_b128 v[200:203], v151
	v_mfma_f32_16x16x32_bf16 v[120:123], v[160:163], v[168:171], 0
	v_mfma_f32_16x16x32_bf16 v[108:111], v[152:155], v[176:179], 0
	ds_read_b128 v[204:207], v151 offset:1024
	v_mfma_f32_16x16x32_bf16 v[104:107], v[160:163], v[176:179], 0
	v_mfma_f32_16x16x32_bf16 v[92:95], v[152:155], v[184:187], 0
	ds_read_b128 v[208:211], v151 offset:2048
	v_mfma_f32_16x16x32_bf16 v[88:91], v[160:163], v[184:187], 0
	v_mfma_f32_16x16x32_bf16 v[76:79], v[152:155], v[192:195], 0
	ds_read_b128 v[212:215], v151 offset:3072
	v_mfma_f32_16x16x32_bf16 v[72:75], v[160:163], v[192:195], 0
	v_mfma_f32_16x16x32_bf16 v[124:127], v[156:159], v[172:175], v[124:127]
	v_mfma_f32_16x16x32_bf16 v[120:123], v[164:167], v[172:175], v[120:123]
	v_mfma_f32_16x16x32_bf16 v[108:111], v[156:159], v[180:183], v[108:111]
	v_mfma_f32_16x16x32_bf16 v[104:107], v[164:167], v[180:183], v[104:107]
	v_mfma_f32_16x16x32_bf16 v[92:95], v[156:159], v[188:191], v[92:95]
	v_mfma_f32_16x16x32_bf16 v[88:91], v[164:167], v[188:191], v[88:91]
	v_mfma_f32_16x16x32_bf16 v[76:79], v[156:159], v[196:199], v[76:79]
	v_mfma_f32_16x16x32_bf16 v[72:75], v[164:167], v[196:199], v[72:75]
	s_barrier
	s_add_i32 s58, s47, s38
	s_add_u32 s80, s26, 0x80
	s_addc_u32 s81, s27, 0
	s_mov_b32 m0, s58
	global_load_lds_dwordx4 v132, s[26:27]
	s_add_i32 m0, s58, 0x2000
	s_nop 0
	global_load_lds_dwordx4 v128, s[26:27]
	s_waitcnt vmcnt(10)
	s_barrier
	s_waitcnt lgkmcnt(0)
	s_waitcnt lgkmcnt(0)
	v_mfma_f32_16x16x32_bf16 v[116:119], v[200:203], v[168:171], 0
	v_mfma_f32_16x16x32_bf16 v[112:115], v[208:211], v[168:171], 0
	v_mfma_f32_16x16x32_bf16 v[100:103], v[200:203], v[176:179], 0
	v_mfma_f32_16x16x32_bf16 v[96:99], v[208:211], v[176:179], 0
	v_mfma_f32_16x16x32_bf16 v[84:87], v[200:203], v[184:187], 0
	v_mfma_f32_16x16x32_bf16 v[80:83], v[208:211], v[184:187], 0
	v_mfma_f32_16x16x32_bf16 v[68:71], v[200:203], v[192:195], 0
	v_mfma_f32_16x16x32_bf16 v[64:67], v[208:211], v[192:195], 0
	v_mfma_f32_16x16x32_bf16 v[116:119], v[204:207], v[172:175], v[116:119]
	v_mfma_f32_16x16x32_bf16 v[112:115], v[212:215], v[172:175], v[112:115]
	v_mfma_f32_16x16x32_bf16 v[100:103], v[204:207], v[180:183], v[100:103]
	v_mfma_f32_16x16x32_bf16 v[96:99], v[212:215], v[180:183], v[96:99]
	v_mfma_f32_16x16x32_bf16 v[84:87], v[204:207], v[188:191], v[84:87]
	v_mfma_f32_16x16x32_bf16 v[80:83], v[212:215], v[188:191], v[80:83]
	v_mfma_f32_16x16x32_bf16 v[68:71], v[204:207], v[196:199], v[68:71]
	v_mfma_f32_16x16x32_bf16 v[64:67], v[212:215], v[196:199], v[64:67]
	s_mov_b32 m0, s19
	s_add_u32 s82, s28, 0x80
	s_addc_u32 s83, s29, 0
	s_barrier
	ds_read_b128 v[168:171], v150 offset:16384
	ds_read_b128 v[172:175], v150 offset:17408
	ds_read_b128 v[176:179], v150 offset:18432
	ds_read_b128 v[180:183], v150 offset:19456
	ds_read_b128 v[184:187], v150 offset:20480
	ds_read_b128 v[188:191], v150 offset:21504
	ds_read_b128 v[192:195], v150 offset:22528
	ds_read_b128 v[196:199], v150 offset:23552
	global_load_lds_dwordx4 v134, s[28:29]
	s_mov_b32 m0, s42
	s_nop 0
	global_load_lds_dwordx4 v130, s[28:29]
	s_barrier
	s_waitcnt lgkmcnt(0)
	s_waitcnt lgkmcnt(0)
	v_mfma_f32_16x16x32_bf16 v[60:63], v[152:155], v[168:171], 0
	v_mfma_f32_16x16x32_bf16 v[56:59], v[160:163], v[168:171], 0
	v_mfma_f32_16x16x32_bf16 v[44:47], v[152:155], v[176:179], 0
	v_mfma_f32_16x16x32_bf16 v[40:43], v[160:163], v[176:179], 0
	v_mfma_f32_16x16x32_bf16 v[28:31], v[152:155], v[184:187], 0
	v_mfma_f32_16x16x32_bf16 v[24:27], v[160:163], v[184:187], 0
	v_mfma_f32_16x16x32_bf16 v[12:15], v[152:155], v[192:195], 0
	v_mfma_f32_16x16x32_bf16 v[8:11], v[160:163], v[192:195], 0
	v_mfma_f32_16x16x32_bf16 v[60:63], v[156:159], v[172:175], v[60:63]
	v_mfma_f32_16x16x32_bf16 v[56:59], v[164:167], v[172:175], v[56:59]
	v_mfma_f32_16x16x32_bf16 v[44:47], v[156:159], v[180:183], v[44:47]
	v_mfma_f32_16x16x32_bf16 v[40:43], v[164:167], v[180:183], v[40:43]
	v_mfma_f32_16x16x32_bf16 v[28:31], v[156:159], v[188:191], v[28:31]
	v_mfma_f32_16x16x32_bf16 v[24:27], v[164:167], v[188:191], v[24:27]
	v_mfma_f32_16x16x32_bf16 v[12:15], v[156:159], v[196:199], v[12:15]
	v_mfma_f32_16x16x32_bf16 v[8:11], v[164:167], v[196:199], v[8:11]
	s_barrier
	s_add_u32 s58, s26, 0x40000
	s_addc_u32 s59, s27, 0
	s_add_i32 s60, s48, s38
	s_mov_b32 m0, s60
	s_nop 0
	global_load_lds_dwordx4 v132, s[58:59]
	s_add_i32 m0, s60, 0x2000
	s_nop 0
	global_load_lds_dwordx4 v128, s[58:59]
	s_waitcnt vmcnt(8)
	s_barrier
	v_mfma_f32_16x16x32_bf16 v[52:55], v[200:203], v[168:171], 0
	v_mfma_f32_16x16x32_bf16 v[48:51], v[208:211], v[168:171], 0
	v_mfma_f32_16x16x32_bf16 v[36:39], v[200:203], v[176:179], 0
	v_mfma_f32_16x16x32_bf16 v[32:35], v[208:211], v[176:179], 0
	v_mfma_f32_16x16x32_bf16 v[20:23], v[200:203], v[184:187], 0
	v_mfma_f32_16x16x32_bf16 v[16:19], v[208:211], v[184:187], 0
	v_mfma_f32_16x16x32_bf16 v[4:7], v[200:203], v[192:195], 0
	v_mfma_f32_16x16x32_bf16 v[0:3], v[208:211], v[192:195], 0
	v_mfma_f32_16x16x32_bf16 v[52:55], v[204:207], v[172:175], v[52:55]
	v_mfma_f32_16x16x32_bf16 v[48:51], v[212:215], v[172:175], v[48:51]
	v_mfma_f32_16x16x32_bf16 v[36:39], v[204:207], v[180:183], v[36:39]
	v_mfma_f32_16x16x32_bf16 v[32:35], v[212:215], v[180:183], v[32:35]
	v_mfma_f32_16x16x32_bf16 v[20:23], v[204:207], v[188:191], v[20:23]
	v_mfma_f32_16x16x32_bf16 v[16:19], v[212:215], v[188:191], v[16:19]
	v_mfma_f32_16x16x32_bf16 v[4:7], v[204:207], v[196:199], v[4:7]
	v_mfma_f32_16x16x32_bf16 v[0:3], v[212:215], v[196:199], v[0:3]
	s_add_i32 s58, 0, 0x18000
	v_add_u32_e32 v164, s58, v145
	s_barrier
	s_branch .Lg131_mid
.LBB0_131:
	ds_read_b128 v[152:155], v149
	ds_read_b128 v[156:159], v149 offset:1024
	ds_read_b128 v[160:163], v149 offset:2048
	ds_read_b128 v[164:167], v149 offset:3072
	s_add_u32 s26, s20, 0xfffc0080
	s_addc_u32 s27, s21, -1
	s_cmp_eq_u32 s57, 12
	s_cselect_b32 s29, s13, s27
	s_cselect_b32 s28, s53, s26
	s_cselect_b32 s27, s11, s56
	s_cselect_b32 s26, s54, s55
	s_add_i32 m0, s19, 0xc000
	ds_read_b128 v[168:171], v150
	ds_read_b128 v[172:175], v150 offset:1024
	ds_read_b128 v[176:179], v150 offset:2048
	ds_read_b128 v[180:183], v150 offset:3072
	ds_read_b128 v[184:187], v150 offset:4096
	ds_read_b128 v[188:191], v150 offset:5120
	ds_read_b128 v[192:195], v150 offset:6144
	ds_read_b128 v[196:199], v150 offset:7168
	global_load_lds_dwordx4 v136, s[20:21]
	s_add_i32 m0, s19, 0xe000
	s_nop 0
	global_load_lds_dwordx4 v138, s[20:21]
	s_waitcnt lgkmcnt(8)
	s_barrier
	s_waitcnt lgkmcnt(0)
	s_waitcnt lgkmcnt(0)
	v_mfma_f32_16x16x32_bf16 v[124:127], v[152:155], v[168:171], v[124:127]
	ds_read_b128 v[200:203], v151
	v_mfma_f32_16x16x32_bf16 v[120:123], v[160:163], v[168:171], v[120:123]
	v_mfma_f32_16x16x32_bf16 v[108:111], v[152:155], v[176:179], v[108:111]
	ds_read_b128 v[204:207], v151 offset:1024
	v_mfma_f32_16x16x32_bf16 v[104:107], v[160:163], v[176:179], v[104:107]
	v_mfma_f32_16x16x32_bf16 v[92:95], v[152:155], v[184:187], v[92:95]
	ds_read_b128 v[208:211], v151 offset:2048
	v_mfma_f32_16x16x32_bf16 v[88:91], v[160:163], v[184:187], v[88:91]
	v_mfma_f32_16x16x32_bf16 v[76:79], v[152:155], v[192:195], v[76:79]
	ds_read_b128 v[212:215], v151 offset:3072
	v_mfma_f32_16x16x32_bf16 v[72:75], v[160:163], v[192:195], v[72:75]
	v_mfma_f32_16x16x32_bf16 v[124:127], v[156:159], v[172:175], v[124:127]
	v_mfma_f32_16x16x32_bf16 v[120:123], v[164:167], v[172:175], v[120:123]
	v_mfma_f32_16x16x32_bf16 v[108:111], v[156:159], v[180:183], v[108:111]
	v_mfma_f32_16x16x32_bf16 v[104:107], v[164:167], v[180:183], v[104:107]
	v_mfma_f32_16x16x32_bf16 v[92:95], v[156:159], v[188:191], v[92:95]
	v_mfma_f32_16x16x32_bf16 v[88:91], v[164:167], v[188:191], v[88:91]
	v_mfma_f32_16x16x32_bf16 v[76:79], v[156:159], v[196:199], v[76:79]
	v_mfma_f32_16x16x32_bf16 v[72:75], v[164:167], v[196:199], v[72:75]
	s_barrier
	s_add_i32 s58, s47, s38
	s_add_u32 s80, s26, 0x80
	s_addc_u32 s81, s27, 0
	s_mov_b32 m0, s58
	global_load_lds_dwordx4 v132, s[26:27]
	s_add_i32 m0, s58, 0x2000
	s_nop 0
	global_load_lds_dwordx4 v128, s[26:27]
	s_waitcnt vmcnt(10)
	s_barrier
	s_waitcnt lgkmcnt(0)
	s_waitcnt lgkmcnt(0)
	v_mfma_f32_16x16x32_bf16 v[116:119], v[200:203], v[168:171], v[116:119]
	v_mfma_f32_16x16x32_bf16 v[112:115], v[208:211], v[168:171], v[112:115]
	v_mfma_f32_16x16x32_bf16 v[100:103], v[200:203], v[176:179], v[100:103]
	v_mfma_f32_16x16x32_bf16 v[96:99], v[208:211], v[176:179], v[96:99]
	v_mfma_f32_16x16x32_bf16 v[84:87], v[200:203], v[184:187], v[84:87]
	v_mfma_f32_16x16x32_bf16 v[80:83], v[208:211], v[184:187], v[80:83]
	v_mfma_f32_16x16x32_bf16 v[68:71], v[200:203], v[192:195], v[68:71]
	v_mfma_f32_16x16x32_bf16 v[64:67], v[208:211], v[192:195], v[64:67]
	v_mfma_f32_16x16x32_bf16 v[116:119], v[204:207], v[172:175], v[116:119]
	v_mfma_f32_16x16x32_bf16 v[112:115], v[212:215], v[172:175], v[112:115]
	v_mfma_f32_16x16x32_bf16 v[100:103], v[204:207], v[180:183], v[100:103]
	v_mfma_f32_16x16x32_bf16 v[96:99], v[212:215], v[180:183], v[96:99]
	v_mfma_f32_16x16x32_bf16 v[84:87], v[204:207], v[188:191], v[84:87]
	v_mfma_f32_16x16x32_bf16 v[80:83], v[212:215], v[188:191], v[80:83]
	v_mfma_f32_16x16x32_bf16 v[68:71], v[204:207], v[196:199], v[68:71]
	v_mfma_f32_16x16x32_bf16 v[64:67], v[212:215], v[196:199], v[64:67]
	s_mov_b32 m0, s19
	s_add_u32 s82, s28, 0x80
	s_addc_u32 s83, s29, 0
	s_barrier
	ds_read_b128 v[168:171], v150 offset:16384
	ds_read_b128 v[172:175], v150 offset:17408
	ds_read_b128 v[176:179], v150 offset:18432
	ds_read_b128 v[180:183], v150 offset:19456
	ds_read_b128 v[184:187], v150 offset:20480
	ds_read_b128 v[188:191], v150 offset:21504
	ds_read_b128 v[192:195], v150 offset:22528
	ds_read_b128 v[196:199], v150 offset:23552
	global_load_lds_dwordx4 v134, s[28:29]
	s_mov_b32 m0, s42
	s_nop 0
	global_load_lds_dwordx4 v130, s[28:29]
	s_barrier
	s_waitcnt lgkmcnt(0)
	s_waitcnt lgkmcnt(0)
	v_mfma_f32_16x16x32_bf16 v[60:63], v[152:155], v[168:171], v[60:63]
	v_mfma_f32_16x16x32_bf16 v[56:59], v[160:163], v[168:171], v[56:59]
	v_mfma_f32_16x16x32_bf16 v[44:47], v[152:155], v[176:179], v[44:47]
	v_mfma_f32_16x16x32_bf16 v[40:43], v[160:163], v[176:179], v[40:43]
	v_mfma_f32_16x16x32_bf16 v[28:31], v[152:155], v[184:187], v[28:31]
	v_mfma_f32_16x16x32_bf16 v[24:27], v[160:163], v[184:187], v[24:27]
	v_mfma_f32_16x16x32_bf16 v[12:15], v[152:155], v[192:195], v[12:15]
	v_mfma_f32_16x16x32_bf16 v[8:11], v[160:163], v[192:195], v[8:11]
	v_mfma_f32_16x16x32_bf16 v[60:63], v[156:159], v[172:175], v[60:63]
	v_mfma_f32_16x16x32_bf16 v[56:59], v[164:167], v[172:175], v[56:59]
	v_mfma_f32_16x16x32_bf16 v[44:47], v[156:159], v[180:183], v[44:47]
	v_mfma_f32_16x16x32_bf16 v[40:43], v[164:167], v[180:183], v[40:43]
	v_mfma_f32_16x16x32_bf16 v[28:31], v[156:159], v[188:191], v[28:31]
	v_mfma_f32_16x16x32_bf16 v[24:27], v[164:167], v[188:191], v[24:27]
	v_mfma_f32_16x16x32_bf16 v[12:15], v[156:159], v[196:199], v[12:15]
	v_mfma_f32_16x16x32_bf16 v[8:11], v[164:167], v[196:199], v[8:11]
	s_barrier
	s_add_u32 s58, s26, 0x40000
	s_addc_u32 s59, s27, 0
	s_add_i32 s60, s48, s38
	s_mov_b32 m0, s60
	s_nop 0
	global_load_lds_dwordx4 v132, s[58:59]
	s_add_i32 m0, s60, 0x2000
	s_nop 0
	global_load_lds_dwordx4 v128, s[58:59]
	s_waitcnt vmcnt(8)
	s_barrier
	v_mfma_f32_16x16x32_bf16 v[52:55], v[200:203], v[168:171], v[52:55]
	v_mfma_f32_16x16x32_bf16 v[48:51], v[208:211], v[168:171], v[48:51]
	v_mfma_f32_16x16x32_bf16 v[36:39], v[200:203], v[176:179], v[36:39]
	v_mfma_f32_16x16x32_bf16 v[32:35], v[208:211], v[176:179], v[32:35]
	v_mfma_f32_16x16x32_bf16 v[20:23], v[200:203], v[184:187], v[20:23]
	v_mfma_f32_16x16x32_bf16 v[16:19], v[208:211], v[184:187], v[16:19]
	v_mfma_f32_16x16x32_bf16 v[4:7], v[200:203], v[192:195], v[4:7]
	v_mfma_f32_16x16x32_bf16 v[0:3], v[208:211], v[192:195], v[0:3]
	v_mfma_f32_16x16x32_bf16 v[52:55], v[204:207], v[172:175], v[52:55]
	v_mfma_f32_16x16x32_bf16 v[48:51], v[212:215], v[172:175], v[48:51]
	v_mfma_f32_16x16x32_bf16 v[36:39], v[204:207], v[180:183], v[36:39]
	v_mfma_f32_16x16x32_bf16 v[32:35], v[212:215], v[180:183], v[32:35]
	v_mfma_f32_16x16x32_bf16 v[20:23], v[204:207], v[188:191], v[20:23]
	v_mfma_f32_16x16x32_bf16 v[16:19], v[212:215], v[188:191], v[16:19]
	v_mfma_f32_16x16x32_bf16 v[4:7], v[204:207], v[196:199], v[4:7]
	v_mfma_f32_16x16x32_bf16 v[0:3], v[212:215], v[196:199], v[0:3]
	s_add_i32 s58, 0, 0x18000
	v_add_u32_e32 v164, s58, v145
	s_barrier
.Lg131_mid:
	ds_read_b128 v[152:155], v164
	ds_read_b128 v[156:159], v164 offset:1024
	ds_read_b128 v[160:163], v164 offset:2048
	ds_read_b128 v[164:167], v164 offset:3072
	s_add_u32 s28, s28, 0x40000
	s_addc_u32 s29, s29, 0
	s_mov_b32 m0, s43
	ds_read_b128 v[168:171], v150 offset:32768
	ds_read_b128 v[172:175], v150 offset:33792
	ds_read_b128 v[176:179], v150 offset:34816
	ds_read_b128 v[180:183], v150 offset:35840
	ds_read_b128 v[184:187], v150 offset:36864
	ds_read_b128 v[188:191], v150 offset:37888
	ds_read_b128 v[192:195], v150 offset:38912
	ds_read_b128 v[196:199], v150 offset:39936
	global_load_lds_dwordx4 v134, s[28:29]
	s_mov_b32 m0, s44
	s_nop 0
	global_load_lds_dwordx4 v130, s[28:29]
	s_waitcnt lgkmcnt(8)
	s_barrier
	s_waitcnt lgkmcnt(0)
	s_waitcnt lgkmcnt(0)
	s_add_i32 s28, 0, 0x1c000
	v_add_u32_e32 v212, s28, v145
	v_mfma_f32_16x16x32_bf16 v[124:127], v[152:155], v[168:171], v[124:127]
	ds_read_b128 v[200:203], v212
	v_mfma_f32_16x16x32_bf16 v[120:123], v[160:163], v[168:171], v[120:123]
	v_mfma_f32_16x16x32_bf16 v[108:111], v[152:155], v[176:179], v[108:111]
	ds_read_b128 v[204:207], v212 offset:1024
	v_mfma_f32_16x16x32_bf16 v[104:107], v[160:163], v[176:179], v[104:107]
	v_mfma_f32_16x16x32_bf16 v[92:95], v[152:155], v[184:187], v[92:95]
	ds_read_b128 v[208:211], v212 offset:2048
	v_mfma_f32_16x16x32_bf16 v[88:91], v[160:163], v[184:187], v[88:91]
	v_mfma_f32_16x16x32_bf16 v[76:79], v[152:155], v[192:195], v[76:79]
	ds_read_b128 v[212:215], v212 offset:3072
	v_mfma_f32_16x16x32_bf16 v[72:75], v[160:163], v[192:195], v[72:75]
	v_mfma_f32_16x16x32_bf16 v[124:127], v[156:159], v[172:175], v[124:127]
	v_mfma_f32_16x16x32_bf16 v[120:123], v[164:167], v[172:175], v[120:123]
	v_mfma_f32_16x16x32_bf16 v[108:111], v[156:159], v[180:183], v[108:111]
	v_mfma_f32_16x16x32_bf16 v[104:107], v[164:167], v[180:183], v[104:107]
	v_mfma_f32_16x16x32_bf16 v[92:95], v[156:159], v[188:191], v[92:95]
	v_mfma_f32_16x16x32_bf16 v[88:91], v[164:167], v[188:191], v[88:91]
	v_mfma_f32_16x16x32_bf16 v[76:79], v[156:159], v[196:199], v[76:79]
	v_mfma_f32_16x16x32_bf16 v[72:75], v[164:167], v[196:199], v[72:75]
	s_barrier
	s_add_i32 s29, s58, s38
	s_mov_b32 m0, s29
	global_load_lds_dwordx4 v132, s[80:81]
	s_add_i32 m0, s29, 0x2000
	s_nop 0
	global_load_lds_dwordx4 v128, s[80:81]
	s_waitcnt vmcnt(10)
	s_barrier
	s_waitcnt lgkmcnt(0)
	s_waitcnt lgkmcnt(0)
	v_mfma_f32_16x16x32_bf16 v[116:119], v[200:203], v[168:171], v[116:119]
	v_mfma_f32_16x16x32_bf16 v[112:115], v[208:211], v[168:171], v[112:115]
	v_mfma_f32_16x16x32_bf16 v[100:103], v[200:203], v[176:179], v[100:103]
	v_mfma_f32_16x16x32_bf16 v[96:99], v[208:211], v[176:179], v[96:99]
	v_mfma_f32_16x16x32_bf16 v[84:87], v[200:203], v[184:187], v[84:87]
	v_mfma_f32_16x16x32_bf16 v[80:83], v[208:211], v[184:187], v[80:83]
	v_mfma_f32_16x16x32_bf16 v[68:71], v[200:203], v[192:195], v[68:71]
	v_mfma_f32_16x16x32_bf16 v[64:67], v[208:211], v[192:195], v[64:67]
	v_mfma_f32_16x16x32_bf16 v[116:119], v[204:207], v[172:175], v[116:119]
	v_mfma_f32_16x16x32_bf16 v[112:115], v[212:215], v[172:175], v[112:115]
	v_mfma_f32_16x16x32_bf16 v[100:103], v[204:207], v[180:183], v[100:103]
	v_mfma_f32_16x16x32_bf16 v[96:99], v[212:215], v[180:183], v[96:99]
	v_mfma_f32_16x16x32_bf16 v[84:87], v[204:207], v[188:191], v[84:87]
	v_mfma_f32_16x16x32_bf16 v[80:83], v[212:215], v[188:191], v[80:83]
	v_mfma_f32_16x16x32_bf16 v[68:71], v[204:207], v[196:199], v[68:71]
	v_mfma_f32_16x16x32_bf16 v[64:67], v[212:215], v[196:199], v[64:67]
	s_mov_b32 m0, s45
	s_barrier
	ds_read_b128 v[168:171], v150 offset:49152
	ds_read_b128 v[172:175], v150 offset:50176
	ds_read_b128 v[176:179], v150 offset:51200
	ds_read_b128 v[180:183], v150 offset:52224
	ds_read_b128 v[184:187], v150 offset:53248
	ds_read_b128 v[188:191], v150 offset:54272
	ds_read_b128 v[192:195], v150 offset:55296
	ds_read_b128 v[196:199], v150 offset:56320
	global_load_lds_dwordx4 v134, s[82:83]
	s_mov_b32 m0, s46
	s_nop 0
	global_load_lds_dwordx4 v130, s[82:83]
	s_barrier
	s_waitcnt lgkmcnt(0)
	s_waitcnt lgkmcnt(0)
	v_mfma_f32_16x16x32_bf16 v[60:63], v[152:155], v[168:171], v[60:63]
	v_mfma_f32_16x16x32_bf16 v[56:59], v[160:163], v[168:171], v[56:59]
	v_mfma_f32_16x16x32_bf16 v[44:47], v[152:155], v[176:179], v[44:47]
	v_mfma_f32_16x16x32_bf16 v[40:43], v[160:163], v[176:179], v[40:43]
	v_mfma_f32_16x16x32_bf16 v[28:31], v[152:155], v[184:187], v[28:31]
	v_mfma_f32_16x16x32_bf16 v[24:27], v[160:163], v[184:187], v[24:27]
	v_mfma_f32_16x16x32_bf16 v[12:15], v[152:155], v[192:195], v[12:15]
	v_mfma_f32_16x16x32_bf16 v[8:11], v[160:163], v[192:195], v[8:11]
	v_mfma_f32_16x16x32_bf16 v[60:63], v[156:159], v[172:175], v[60:63]
	v_mfma_f32_16x16x32_bf16 v[56:59], v[164:167], v[172:175], v[56:59]
	v_mfma_f32_16x16x32_bf16 v[44:47], v[156:159], v[180:183], v[44:47]
	v_mfma_f32_16x16x32_bf16 v[40:43], v[164:167], v[180:183], v[40:43]
	v_mfma_f32_16x16x32_bf16 v[28:31], v[156:159], v[188:191], v[28:31]
	v_mfma_f32_16x16x32_bf16 v[24:27], v[164:167], v[188:191], v[24:27]
	v_mfma_f32_16x16x32_bf16 v[12:15], v[156:159], v[196:199], v[12:15]
	v_mfma_f32_16x16x32_bf16 v[8:11], v[164:167], v[196:199], v[8:11]
	s_barrier
	s_add_u32 s26, s26, 0x40080
	s_addc_u32 s27, s27, 0
	s_add_i32 s28, s28, s38
	s_mov_b32 m0, s28
	s_nop 0
	global_load_lds_dwordx4 v132, s[26:27]
	s_add_i32 m0, s28, 0x2000
	s_nop 0
	global_load_lds_dwordx4 v128, s[26:27]
	s_waitcnt vmcnt(8)
	s_barrier
	v_mfma_f32_16x16x32_bf16 v[52:55], v[200:203], v[168:171], v[52:55]
	v_mfma_f32_16x16x32_bf16 v[48:51], v[208:211], v[168:171], v[48:51]
	v_mfma_f32_16x16x32_bf16 v[36:39], v[200:203], v[176:179], v[36:39]
	v_mfma_f32_16x16x32_bf16 v[32:35], v[208:211], v[176:179], v[32:35]
	v_mfma_f32_16x16x32_bf16 v[20:23], v[200:203], v[184:187], v[20:23]
	v_mfma_f32_16x16x32_bf16 v[16:19], v[208:211], v[184:187], v[16:19]
	v_mfma_f32_16x16x32_bf16 v[4:7], v[200:203], v[192:195], v[4:7]
	v_mfma_f32_16x16x32_bf16 v[0:3], v[208:211], v[192:195], v[0:3]
	v_mfma_f32_16x16x32_bf16 v[52:55], v[204:207], v[172:175], v[52:55]
	v_mfma_f32_16x16x32_bf16 v[48:51], v[212:215], v[172:175], v[48:51]
	v_mfma_f32_16x16x32_bf16 v[36:39], v[204:207], v[180:183], v[36:39]
	v_mfma_f32_16x16x32_bf16 v[32:35], v[212:215], v[180:183], v[32:35]
	v_mfma_f32_16x16x32_bf16 v[20:23], v[204:207], v[188:191], v[20:23]
	v_mfma_f32_16x16x32_bf16 v[16:19], v[212:215], v[188:191], v[16:19]
	v_mfma_f32_16x16x32_bf16 v[4:7], v[204:207], v[196:199], v[4:7]
	v_mfma_f32_16x16x32_bf16 v[0:3], v[212:215], v[196:199], v[0:3]
	s_add_i32 s57, s57, 2
	s_add_u32 s20, s20, 0x100
	s_addc_u32 s21, s21, 0
	s_add_u32 s55, s55, 0x100
	s_addc_u32 s56, s56, 0
	s_cmp_gt_u32 s57, 13
	s_barrier
	s_cbranch_scc0 .LBB0_131
	s_setprio 0
	s_cmpk_gt_u32 s37, 0xff
	s_cbranch_scc1 .Lg131_nox
	s_barrier
	s_setprio 1

.Lg248_noy:
	ds_read_b128 v[144:147], v151
	ds_read_b128 v[156:159], v151 offset:1024
	ds_read_b128 v[160:163], v151 offset:2048
	ds_read_b128 v[164:167], v151 offset:3072
	s_add_u32 s26, s20, 0x100
	s_addc_u32 s27, s21, 0
	s_cmp_eq_u32 s59, 40
	s_cselect_b32 s31, s9, s27
	s_cselect_b32 s30, s8, s26
	s_cselect_b32 s29, s11, s58
	s_cselect_b32 s28, s10, s57
	s_add_i32 m0, s41, 0xc000
	ds_read_b128 v[168:171], v152
	ds_read_b128 v[172:175], v152 offset:1024
	ds_read_b128 v[176:179], v152 offset:2048
	ds_read_b128 v[180:183], v152 offset:3072
	ds_read_b128 v[184:187], v152 offset:4096
	ds_read_b128 v[188:191], v152 offset:5120
	ds_read_b128 v[192:195], v152 offset:6144
	ds_read_b128 v[196:199], v152 offset:7168
	global_load_lds_dwordx4 v136, s[20:21]
	s_add_i32 m0, s41, 0xe000
	s_nop 0
	global_load_lds_dwordx4 v138, s[20:21]
	s_waitcnt lgkmcnt(8)
	s_barrier
	s_waitcnt lgkmcnt(0)
	s_waitcnt lgkmcnt(0)
	v_mfma_f32_16x16x32_bf16 v[124:127], v[144:147], v[168:171], 0
	ds_read_b128 v[200:203], v153
	v_mfma_f32_16x16x32_bf16 v[120:123], v[160:163], v[168:171], 0
	v_mfma_f32_16x16x32_bf16 v[108:111], v[144:147], v[176:179], 0
	ds_read_b128 v[204:207], v153 offset:1024
	v_mfma_f32_16x16x32_bf16 v[104:107], v[160:163], v[176:179], 0
	v_mfma_f32_16x16x32_bf16 v[92:95], v[144:147], v[184:187], 0
	ds_read_b128 v[208:211], v153 offset:2048
	v_mfma_f32_16x16x32_bf16 v[88:91], v[160:163], v[184:187], 0
	v_mfma_f32_16x16x32_bf16 v[76:79], v[144:147], v[192:195], 0
	ds_read_b128 v[212:215], v153 offset:3072
	v_mfma_f32_16x16x32_bf16 v[72:75], v[160:163], v[192:195], 0
	v_mfma_f32_16x16x32_bf16 v[124:127], v[156:159], v[172:175], v[124:127]
	v_mfma_f32_16x16x32_bf16 v[120:123], v[164:167], v[172:175], v[120:123]
	v_mfma_f32_16x16x32_bf16 v[108:111], v[156:159], v[180:183], v[108:111]
	v_mfma_f32_16x16x32_bf16 v[104:107], v[164:167], v[180:183], v[104:107]
	v_mfma_f32_16x16x32_bf16 v[92:95], v[156:159], v[188:191], v[92:95]
	v_mfma_f32_16x16x32_bf16 v[88:91], v[164:167], v[188:191], v[88:91]
	v_mfma_f32_16x16x32_bf16 v[76:79], v[156:159], v[196:199], v[76:79]
	v_mfma_f32_16x16x32_bf16 v[72:75], v[164:167], v[196:199], v[72:75]
	s_barrier
	s_add_i32 s20, s51, s40
	s_add_u32 s80, s28, 0x80
	s_addc_u32 s81, s29, 0
	s_mov_b32 m0, s20
	global_load_lds_dwordx4 v130, s[28:29]
	s_add_i32 m0, s20, 0x2000
	s_nop 0
	global_load_lds_dwordx4 v134, s[28:29]
	s_waitcnt vmcnt(10)
	s_barrier
	s_waitcnt lgkmcnt(0)
	s_waitcnt lgkmcnt(0)
	v_mfma_f32_16x16x32_bf16 v[116:119], v[200:203], v[168:171], 0
	v_mfma_f32_16x16x32_bf16 v[112:115], v[208:211], v[168:171], 0
	v_mfma_f32_16x16x32_bf16 v[100:103], v[200:203], v[176:179], 0
	v_mfma_f32_16x16x32_bf16 v[96:99], v[208:211], v[176:179], 0
	v_mfma_f32_16x16x32_bf16 v[84:87], v[200:203], v[184:187], 0
	v_mfma_f32_16x16x32_bf16 v[80:83], v[208:211], v[184:187], 0
	v_mfma_f32_16x16x32_bf16 v[68:71], v[200:203], v[192:195], 0
	v_mfma_f32_16x16x32_bf16 v[64:67], v[208:211], v[192:195], 0
	v_mfma_f32_16x16x32_bf16 v[116:119], v[204:207], v[172:175], v[116:119]
	v_mfma_f32_16x16x32_bf16 v[112:115], v[212:215], v[172:175], v[112:115]
	v_mfma_f32_16x16x32_bf16 v[100:103], v[204:207], v[180:183], v[100:103]
	v_mfma_f32_16x16x32_bf16 v[96:99], v[212:215], v[180:183], v[96:99]
	v_mfma_f32_16x16x32_bf16 v[84:87], v[204:207], v[188:191], v[84:87]
	v_mfma_f32_16x16x32_bf16 v[80:83], v[212:215], v[188:191], v[80:83]
	v_mfma_f32_16x16x32_bf16 v[68:71], v[204:207], v[196:199], v[68:71]
	v_mfma_f32_16x16x32_bf16 v[64:67], v[212:215], v[196:199], v[64:67]
	s_mov_b32 m0, s41
	s_add_u32 s82, s30, 0x80
	s_addc_u32 s83, s31, 0
	s_barrier
	ds_read_b128 v[168:171], v152 offset:16384
	ds_read_b128 v[172:175], v152 offset:17408
	ds_read_b128 v[176:179], v152 offset:18432
	ds_read_b128 v[180:183], v152 offset:19456
	ds_read_b128 v[184:187], v152 offset:20480
	ds_read_b128 v[188:191], v152 offset:21504
	ds_read_b128 v[192:195], v152 offset:22528
	ds_read_b128 v[196:199], v152 offset:23552
	global_load_lds_dwordx4 v128, s[30:31]
	s_mov_b32 m0, s42
	s_nop 0
	global_load_lds_dwordx4 v132, s[30:31]
	s_barrier
	s_waitcnt lgkmcnt(0)
	s_waitcnt lgkmcnt(0)
	v_mfma_f32_16x16x32_bf16 v[60:63], v[144:147], v[168:171], 0
	v_mfma_f32_16x16x32_bf16 v[56:59], v[160:163], v[168:171], 0
	v_mfma_f32_16x16x32_bf16 v[44:47], v[144:147], v[176:179], 0
	v_mfma_f32_16x16x32_bf16 v[40:43], v[160:163], v[176:179], 0
	v_mfma_f32_16x16x32_bf16 v[28:31], v[144:147], v[184:187], 0
	v_mfma_f32_16x16x32_bf16 v[24:27], v[160:163], v[184:187], 0
	v_mfma_f32_16x16x32_bf16 v[12:15], v[144:147], v[192:195], 0
	v_mfma_f32_16x16x32_bf16 v[8:11], v[160:163], v[192:195], 0
	v_mfma_f32_16x16x32_bf16 v[60:63], v[156:159], v[172:175], v[60:63]
	v_mfma_f32_16x16x32_bf16 v[56:59], v[164:167], v[172:175], v[56:59]
	v_mfma_f32_16x16x32_bf16 v[44:47], v[156:159], v[180:183], v[44:47]
	v_mfma_f32_16x16x32_bf16 v[40:43], v[164:167], v[180:183], v[40:43]
	v_mfma_f32_16x16x32_bf16 v[28:31], v[156:159], v[188:191], v[28:31]
	v_mfma_f32_16x16x32_bf16 v[24:27], v[164:167], v[188:191], v[24:27]
	v_mfma_f32_16x16x32_bf16 v[12:15], v[156:159], v[196:199], v[12:15]
	v_mfma_f32_16x16x32_bf16 v[8:11], v[164:167], v[196:199], v[8:11]
	s_barrier
	s_add_u32 s20, s28, 0xb0000
	s_addc_u32 s21, s29, 0
	s_add_i32 s60, s52, s40
	s_mov_b32 m0, s60
	s_nop 0
	global_load_lds_dwordx4 v130, s[20:21]
	s_add_i32 m0, s60, 0x2000
	s_nop 0
	global_load_lds_dwordx4 v134, s[20:21]
	s_waitcnt vmcnt(8)
	s_barrier
	v_mfma_f32_16x16x32_bf16 v[52:55], v[200:203], v[168:171], 0
	v_mfma_f32_16x16x32_bf16 v[48:51], v[208:211], v[168:171], 0
	v_mfma_f32_16x16x32_bf16 v[36:39], v[200:203], v[176:179], 0
	v_mfma_f32_16x16x32_bf16 v[32:35], v[208:211], v[176:179], 0
	v_mfma_f32_16x16x32_bf16 v[20:23], v[200:203], v[184:187], 0
	v_mfma_f32_16x16x32_bf16 v[16:19], v[208:211], v[184:187], 0
	v_mfma_f32_16x16x32_bf16 v[4:7], v[200:203], v[192:195], 0
	v_mfma_f32_16x16x32_bf16 v[0:3], v[208:211], v[192:195], 0
	v_mfma_f32_16x16x32_bf16 v[52:55], v[204:207], v[172:175], v[52:55]
	v_mfma_f32_16x16x32_bf16 v[48:51], v[212:215], v[172:175], v[48:51]
	v_mfma_f32_16x16x32_bf16 v[36:39], v[204:207], v[180:183], v[36:39]
	v_mfma_f32_16x16x32_bf16 v[32:35], v[212:215], v[180:183], v[32:35]
	v_mfma_f32_16x16x32_bf16 v[20:23], v[204:207], v[188:191], v[20:23]
	v_mfma_f32_16x16x32_bf16 v[16:19], v[212:215], v[188:191], v[16:19]
	v_mfma_f32_16x16x32_bf16 v[4:7], v[204:207], v[196:199], v[4:7]
	v_mfma_f32_16x16x32_bf16 v[0:3], v[212:215], v[196:199], v[0:3]
	s_add_i32 s60, 0, 0x18000
	v_add_u32_e32 v155, s60, v149
	s_barrier
	s_branch .Lg248_mid
.LBB0_248:
	ds_read_b128 v[144:147], v151
	ds_read_b128 v[156:159], v151 offset:1024
	ds_read_b128 v[160:163], v151 offset:2048
	ds_read_b128 v[164:167], v151 offset:3072
	s_add_u32 s26, s20, 0x100
	s_addc_u32 s27, s21, 0
	s_cmp_eq_u32 s59, 40
	s_cselect_b32 s31, s9, s27
	s_cselect_b32 s30, s8, s26
	s_cselect_b32 s29, s11, s58
	s_cselect_b32 s28, s10, s57
	s_add_i32 m0, s41, 0xc000
	ds_read_b128 v[168:171], v152
	ds_read_b128 v[172:175], v152 offset:1024
	ds_read_b128 v[176:179], v152 offset:2048
	ds_read_b128 v[180:183], v152 offset:3072
	ds_read_b128 v[184:187], v152 offset:4096
	ds_read_b128 v[188:191], v152 offset:5120
	ds_read_b128 v[192:195], v152 offset:6144
	ds_read_b128 v[196:199], v152 offset:7168
	global_load_lds_dwordx4 v136, s[20:21]
	s_add_i32 m0, s41, 0xe000
	s_nop 0
	global_load_lds_dwordx4 v138, s[20:21]
	s_waitcnt lgkmcnt(8)
	s_barrier
	s_waitcnt lgkmcnt(0)
	s_waitcnt lgkmcnt(0)
	v_mfma_f32_16x16x32_bf16 v[124:127], v[144:147], v[168:171], v[124:127]
	ds_read_b128 v[200:203], v153
	v_mfma_f32_16x16x32_bf16 v[120:123], v[160:163], v[168:171], v[120:123]
	v_mfma_f32_16x16x32_bf16 v[108:111], v[144:147], v[176:179], v[108:111]
	ds_read_b128 v[204:207], v153 offset:1024
	v_mfma_f32_16x16x32_bf16 v[104:107], v[160:163], v[176:179], v[104:107]
	v_mfma_f32_16x16x32_bf16 v[92:95], v[144:147], v[184:187], v[92:95]
	ds_read_b128 v[208:211], v153 offset:2048
	v_mfma_f32_16x16x32_bf16 v[88:91], v[160:163], v[184:187], v[88:91]
	v_mfma_f32_16x16x32_bf16 v[76:79], v[144:147], v[192:195], v[76:79]
	ds_read_b128 v[212:215], v153 offset:3072
	v_mfma_f32_16x16x32_bf16 v[72:75], v[160:163], v[192:195], v[72:75]
	v_mfma_f32_16x16x32_bf16 v[124:127], v[156:159], v[172:175], v[124:127]
	v_mfma_f32_16x16x32_bf16 v[120:123], v[164:167], v[172:175], v[120:123]
	v_mfma_f32_16x16x32_bf16 v[108:111], v[156:159], v[180:183], v[108:111]
	v_mfma_f32_16x16x32_bf16 v[104:107], v[164:167], v[180:183], v[104:107]
	v_mfma_f32_16x16x32_bf16 v[92:95], v[156:159], v[188:191], v[92:95]
	v_mfma_f32_16x16x32_bf16 v[88:91], v[164:167], v[188:191], v[88:91]
	v_mfma_f32_16x16x32_bf16 v[76:79], v[156:159], v[196:199], v[76:79]
	v_mfma_f32_16x16x32_bf16 v[72:75], v[164:167], v[196:199], v[72:75]
	s_barrier
	s_add_i32 s20, s51, s40
	s_add_u32 s80, s28, 0x80
	s_addc_u32 s81, s29, 0
	s_mov_b32 m0, s20
	global_load_lds_dwordx4 v130, s[28:29]
	s_add_i32 m0, s20, 0x2000
	s_nop 0
	global_load_lds_dwordx4 v134, s[28:29]
	s_waitcnt vmcnt(10)
	s_barrier
	s_waitcnt lgkmcnt(0)
	s_waitcnt lgkmcnt(0)
	v_mfma_f32_16x16x32_bf16 v[116:119], v[200:203], v[168:171], v[116:119]
	v_mfma_f32_16x16x32_bf16 v[112:115], v[208:211], v[168:171], v[112:115]
	v_mfma_f32_16x16x32_bf16 v[100:103], v[200:203], v[176:179], v[100:103]
	v_mfma_f32_16x16x32_bf16 v[96:99], v[208:211], v[176:179], v[96:99]
	v_mfma_f32_16x16x32_bf16 v[84:87], v[200:203], v[184:187], v[84:87]
	v_mfma_f32_16x16x32_bf16 v[80:83], v[208:211], v[184:187], v[80:83]
	v_mfma_f32_16x16x32_bf16 v[68:71], v[200:203], v[192:195], v[68:71]
	v_mfma_f32_16x16x32_bf16 v[64:67], v[208:211], v[192:195], v[64:67]
	v_mfma_f32_16x16x32_bf16 v[116:119], v[204:207], v[172:175], v[116:119]
	v_mfma_f32_16x16x32_bf16 v[112:115], v[212:215], v[172:175], v[112:115]
	v_mfma_f32_16x16x32_bf16 v[100:103], v[204:207], v[180:183], v[100:103]
	v_mfma_f32_16x16x32_bf16 v[96:99], v[212:215], v[180:183], v[96:99]
	v_mfma_f32_16x16x32_bf16 v[84:87], v[204:207], v[188:191], v[84:87]
	v_mfma_f32_16x16x32_bf16 v[80:83], v[212:215], v[188:191], v[80:83]
	v_mfma_f32_16x16x32_bf16 v[68:71], v[204:207], v[196:199], v[68:71]
	v_mfma_f32_16x16x32_bf16 v[64:67], v[212:215], v[196:199], v[64:67]
	s_mov_b32 m0, s41
	s_add_u32 s82, s30, 0x80
	s_addc_u32 s83, s31, 0
	s_barrier
	ds_read_b128 v[168:171], v152 offset:16384
	ds_read_b128 v[172:175], v152 offset:17408
	ds_read_b128 v[176:179], v152 offset:18432
	ds_read_b128 v[180:183], v152 offset:19456
	ds_read_b128 v[184:187], v152 offset:20480
	ds_read_b128 v[188:191], v152 offset:21504
	ds_read_b128 v[192:195], v152 offset:22528
	ds_read_b128 v[196:199], v152 offset:23552
	global_load_lds_dwordx4 v128, s[30:31]
	s_mov_b32 m0, s42
	s_nop 0
	global_load_lds_dwordx4 v132, s[30:31]
	s_barrier
	s_waitcnt lgkmcnt(0)
	s_waitcnt lgkmcnt(0)
	v_mfma_f32_16x16x32_bf16 v[60:63], v[144:147], v[168:171], v[60:63]
	v_mfma_f32_16x16x32_bf16 v[56:59], v[160:163], v[168:171], v[56:59]
	v_mfma_f32_16x16x32_bf16 v[44:47], v[144:147], v[176:179], v[44:47]
	v_mfma_f32_16x16x32_bf16 v[40:43], v[160:163], v[176:179], v[40:43]
	v_mfma_f32_16x16x32_bf16 v[28:31], v[144:147], v[184:187], v[28:31]
	v_mfma_f32_16x16x32_bf16 v[24:27], v[160:163], v[184:187], v[24:27]
	v_mfma_f32_16x16x32_bf16 v[12:15], v[144:147], v[192:195], v[12:15]
	v_mfma_f32_16x16x32_bf16 v[8:11], v[160:163], v[192:195], v[8:11]
	v_mfma_f32_16x16x32_bf16 v[60:63], v[156:159], v[172:175], v[60:63]
	v_mfma_f32_16x16x32_bf16 v[56:59], v[164:167], v[172:175], v[56:59]
	v_mfma_f32_16x16x32_bf16 v[44:47], v[156:159], v[180:183], v[44:47]
	v_mfma_f32_16x16x32_bf16 v[40:43], v[164:167], v[180:183], v[40:43]
	v_mfma_f32_16x16x32_bf16 v[28:31], v[156:159], v[188:191], v[28:31]
	v_mfma_f32_16x16x32_bf16 v[24:27], v[164:167], v[188:191], v[24:27]
	v_mfma_f32_16x16x32_bf16 v[12:15], v[156:159], v[196:199], v[12:15]
	v_mfma_f32_16x16x32_bf16 v[8:11], v[164:167], v[196:199], v[8:11]
	s_barrier
	s_add_u32 s20, s28, 0xb0000
	s_addc_u32 s21, s29, 0
	s_add_i32 s60, s52, s40
	s_mov_b32 m0, s60
	s_nop 0
	global_load_lds_dwordx4 v130, s[20:21]
	s_add_i32 m0, s60, 0x2000
	s_nop 0
	global_load_lds_dwordx4 v134, s[20:21]
	s_waitcnt vmcnt(8)
	s_barrier
	v_mfma_f32_16x16x32_bf16 v[52:55], v[200:203], v[168:171], v[52:55]
	v_mfma_f32_16x16x32_bf16 v[48:51], v[208:211], v[168:171], v[48:51]
	v_mfma_f32_16x16x32_bf16 v[36:39], v[200:203], v[176:179], v[36:39]
	v_mfma_f32_16x16x32_bf16 v[32:35], v[208:211], v[176:179], v[32:35]
	v_mfma_f32_16x16x32_bf16 v[20:23], v[200:203], v[184:187], v[20:23]
	v_mfma_f32_16x16x32_bf16 v[16:19], v[208:211], v[184:187], v[16:19]
	v_mfma_f32_16x16x32_bf16 v[4:7], v[200:203], v[192:195], v[4:7]
	v_mfma_f32_16x16x32_bf16 v[0:3], v[208:211], v[192:195], v[0:3]
	v_mfma_f32_16x16x32_bf16 v[52:55], v[204:207], v[172:175], v[52:55]
	v_mfma_f32_16x16x32_bf16 v[48:51], v[212:215], v[172:175], v[48:51]
	v_mfma_f32_16x16x32_bf16 v[36:39], v[204:207], v[180:183], v[36:39]
	v_mfma_f32_16x16x32_bf16 v[32:35], v[212:215], v[180:183], v[32:35]
	v_mfma_f32_16x16x32_bf16 v[20:23], v[204:207], v[188:191], v[20:23]
	v_mfma_f32_16x16x32_bf16 v[16:19], v[212:215], v[188:191], v[16:19]
	v_mfma_f32_16x16x32_bf16 v[4:7], v[204:207], v[196:199], v[4:7]
	v_mfma_f32_16x16x32_bf16 v[0:3], v[212:215], v[196:199], v[0:3]
	s_add_i32 s60, 0, 0x18000
	v_add_u32_e32 v155, s60, v149
	s_barrier
.Lg248_mid:
	ds_read_b128 v[144:147], v155
	ds_read_b128 v[156:159], v155 offset:1024
	ds_read_b128 v[160:163], v155 offset:2048
	ds_read_b128 v[164:167], v155 offset:3072
	s_add_u32 s20, s30, 0xb0000
	s_addc_u32 s21, s31, 0
	s_mov_b32 m0, s43
	ds_read_b128 v[168:171], v152 offset:32768
	ds_read_b128 v[172:175], v152 offset:33792
	ds_read_b128 v[176:179], v152 offset:34816
	ds_read_b128 v[180:183], v152 offset:35840
	ds_read_b128 v[184:187], v152 offset:36864
	ds_read_b128 v[188:191], v152 offset:37888
	ds_read_b128 v[192:195], v152 offset:38912
	ds_read_b128 v[196:199], v152 offset:39936
	global_load_lds_dwordx4 v128, s[20:21]
	s_mov_b32 m0, s44
	s_nop 0
	global_load_lds_dwordx4 v132, s[20:21]
	s_waitcnt lgkmcnt(8)
	s_barrier
	s_waitcnt lgkmcnt(0)
	s_waitcnt lgkmcnt(0)
	s_add_i32 s30, 0, 0x1c000
	v_add_u32_e32 v155, s30, v149
	v_mfma_f32_16x16x32_bf16 v[124:127], v[144:147], v[168:171], v[124:127]
	ds_read_b128 v[200:203], v155
	v_mfma_f32_16x16x32_bf16 v[120:123], v[160:163], v[168:171], v[120:123]
	v_mfma_f32_16x16x32_bf16 v[108:111], v[144:147], v[176:179], v[108:111]
	ds_read_b128 v[204:207], v155 offset:1024
	v_mfma_f32_16x16x32_bf16 v[104:107], v[160:163], v[176:179], v[104:107]
	v_mfma_f32_16x16x32_bf16 v[92:95], v[144:147], v[184:187], v[92:95]
	ds_read_b128 v[208:211], v155 offset:2048
	v_mfma_f32_16x16x32_bf16 v[88:91], v[160:163], v[184:187], v[88:91]
	v_mfma_f32_16x16x32_bf16 v[76:79], v[144:147], v[192:195], v[76:79]
	ds_read_b128 v[212:215], v155 offset:3072
	v_mfma_f32_16x16x32_bf16 v[72:75], v[160:163], v[192:195], v[72:75]
	v_mfma_f32_16x16x32_bf16 v[124:127], v[156:159], v[172:175], v[124:127]
	v_mfma_f32_16x16x32_bf16 v[120:123], v[164:167], v[172:175], v[120:123]
	v_mfma_f32_16x16x32_bf16 v[108:111], v[156:159], v[180:183], v[108:111]
	v_mfma_f32_16x16x32_bf16 v[104:107], v[164:167], v[180:183], v[104:107]
	v_mfma_f32_16x16x32_bf16 v[92:95], v[156:159], v[188:191], v[92:95]
	v_mfma_f32_16x16x32_bf16 v[88:91], v[164:167], v[188:191], v[88:91]
	v_mfma_f32_16x16x32_bf16 v[76:79], v[156:159], v[196:199], v[76:79]
	v_mfma_f32_16x16x32_bf16 v[72:75], v[164:167], v[196:199], v[72:75]
	s_barrier
	s_add_i32 s20, s60, s40
	s_mov_b32 m0, s20
	global_load_lds_dwordx4 v130, s[80:81]
	s_add_i32 m0, s20, 0x2000
	s_nop 0
	global_load_lds_dwordx4 v134, s[80:81]
	s_waitcnt vmcnt(10)
	s_barrier
	s_waitcnt lgkmcnt(0)
	s_waitcnt lgkmcnt(0)
	v_mfma_f32_16x16x32_bf16 v[116:119], v[200:203], v[168:171], v[116:119]
	v_mfma_f32_16x16x32_bf16 v[112:115], v[208:211], v[168:171], v[112:115]
	v_mfma_f32_16x16x32_bf16 v[100:103], v[200:203], v[176:179], v[100:103]
	v_mfma_f32_16x16x32_bf16 v[96:99], v[208:211], v[176:179], v[96:99]
	v_mfma_f32_16x16x32_bf16 v[84:87], v[200:203], v[184:187], v[84:87]
	v_mfma_f32_16x16x32_bf16 v[80:83], v[208:211], v[184:187], v[80:83]
	v_mfma_f32_16x16x32_bf16 v[68:71], v[200:203], v[192:195], v[68:71]
	v_mfma_f32_16x16x32_bf16 v[64:67], v[208:211], v[192:195], v[64:67]
	v_mfma_f32_16x16x32_bf16 v[116:119], v[204:207], v[172:175], v[116:119]
	v_mfma_f32_16x16x32_bf16 v[112:115], v[212:215], v[172:175], v[112:115]
	v_mfma_f32_16x16x32_bf16 v[100:103], v[204:207], v[180:183], v[100:103]
	v_mfma_f32_16x16x32_bf16 v[96:99], v[212:215], v[180:183], v[96:99]
	v_mfma_f32_16x16x32_bf16 v[84:87], v[204:207], v[188:191], v[84:87]
	v_mfma_f32_16x16x32_bf16 v[80:83], v[212:215], v[188:191], v[80:83]
	v_mfma_f32_16x16x32_bf16 v[68:71], v[204:207], v[196:199], v[68:71]
	v_mfma_f32_16x16x32_bf16 v[64:67], v[212:215], v[196:199], v[64:67]
	s_mov_b32 m0, s46
	s_barrier
	ds_read_b128 v[168:171], v152 offset:49152
	ds_read_b128 v[172:175], v152 offset:50176
	ds_read_b128 v[176:179], v152 offset:51200
	ds_read_b128 v[180:183], v152 offset:52224
	ds_read_b128 v[184:187], v152 offset:53248
	ds_read_b128 v[188:191], v152 offset:54272
	ds_read_b128 v[192:195], v152 offset:55296
	ds_read_b128 v[196:199], v152 offset:56320
	global_load_lds_dwordx4 v128, s[82:83]
	s_mov_b32 m0, s47
	s_nop 0
	global_load_lds_dwordx4 v132, s[82:83]
	s_barrier
	s_waitcnt lgkmcnt(0)
	s_waitcnt lgkmcnt(0)
	v_mfma_f32_16x16x32_bf16 v[60:63], v[144:147], v[168:171], v[60:63]
	v_mfma_f32_16x16x32_bf16 v[56:59], v[160:163], v[168:171], v[56:59]
	v_mfma_f32_16x16x32_bf16 v[44:47], v[144:147], v[176:179], v[44:47]
	v_mfma_f32_16x16x32_bf16 v[40:43], v[160:163], v[176:179], v[40:43]
	v_mfma_f32_16x16x32_bf16 v[28:31], v[144:147], v[184:187], v[28:31]
	v_mfma_f32_16x16x32_bf16 v[24:27], v[160:163], v[184:187], v[24:27]
	v_mfma_f32_16x16x32_bf16 v[12:15], v[144:147], v[192:195], v[12:15]
	v_mfma_f32_16x16x32_bf16 v[8:11], v[160:163], v[192:195], v[8:11]
	v_mfma_f32_16x16x32_bf16 v[60:63], v[156:159], v[172:175], v[60:63]
	v_mfma_f32_16x16x32_bf16 v[56:59], v[164:167], v[172:175], v[56:59]
	v_mfma_f32_16x16x32_bf16 v[44:47], v[156:159], v[180:183], v[44:47]
	v_mfma_f32_16x16x32_bf16 v[40:43], v[164:167], v[180:183], v[40:43]
	v_mfma_f32_16x16x32_bf16 v[28:31], v[156:159], v[188:191], v[28:31]
	v_mfma_f32_16x16x32_bf16 v[24:27], v[164:167], v[188:191], v[24:27]
	v_mfma_f32_16x16x32_bf16 v[12:15], v[156:159], v[196:199], v[12:15]
	v_mfma_f32_16x16x32_bf16 v[8:11], v[164:167], v[196:199], v[8:11]
	s_barrier
	s_add_u32 s20, s28, 0xb0080
	s_addc_u32 s21, s29, 0
	s_add_i32 s28, s30, s40
	s_mov_b32 m0, s28
	s_nop 0
	global_load_lds_dwordx4 v130, s[20:21]
	s_add_i32 m0, s28, 0x2000
	s_nop 0
	global_load_lds_dwordx4 v134, s[20:21]
	s_waitcnt vmcnt(8)
	s_barrier
	v_mfma_f32_16x16x32_bf16 v[52:55], v[200:203], v[168:171], v[52:55]
	v_mfma_f32_16x16x32_bf16 v[48:51], v[208:211], v[168:171], v[48:51]
	v_mfma_f32_16x16x32_bf16 v[36:39], v[200:203], v[176:179], v[36:39]
	v_mfma_f32_16x16x32_bf16 v[32:35], v[208:211], v[176:179], v[32:35]
	v_mfma_f32_16x16x32_bf16 v[20:23], v[200:203], v[184:187], v[20:23]
	v_mfma_f32_16x16x32_bf16 v[16:19], v[208:211], v[184:187], v[16:19]
	v_mfma_f32_16x16x32_bf16 v[4:7], v[200:203], v[192:195], v[4:7]
	v_mfma_f32_16x16x32_bf16 v[0:3], v[208:211], v[192:195], v[0:3]
	v_mfma_f32_16x16x32_bf16 v[52:55], v[204:207], v[172:175], v[52:55]
	v_mfma_f32_16x16x32_bf16 v[48:51], v[212:215], v[172:175], v[48:51]
	v_mfma_f32_16x16x32_bf16 v[36:39], v[204:207], v[180:183], v[36:39]
	v_mfma_f32_16x16x32_bf16 v[32:35], v[212:215], v[180:183], v[32:35]
	v_mfma_f32_16x16x32_bf16 v[20:23], v[204:207], v[188:191], v[20:23]
	v_mfma_f32_16x16x32_bf16 v[16:19], v[212:215], v[188:191], v[16:19]
	v_mfma_f32_16x16x32_bf16 v[4:7], v[204:207], v[196:199], v[4:7]
	v_mfma_f32_16x16x32_bf16 v[0:3], v[212:215], v[196:199], v[0:3]
	s_add_i32 s59, s59, 2
	s_add_u32 s57, s57, 0x100
	s_addc_u32 s58, s58, 0
	s_cmp_gt_u32 s59, 41
	s_mov_b64 s[20:21], s[26:27]
	s_barrier
	s_cbranch_scc0 .LBB0_248
	s_setprio 0
	v_lshl_add_u32 v146, s56, 8, v148
	v_ashrrev_i32_e32 v147, 31, v146
	v_lshl_or_b32 v144, s12, 8, v150
	v_lshlrev_b64 v[156:157], 11, v[146:147]
	v_ashrrev_i32_e32 v145, 31, v144
	v_lshl_add_u64 v[156:157], s[14:15], 0, v[156:157]
	v_lshl_add_u64 v[166:167], v[144:145], 1, v[156:157]
	global_load_dwordx4 v[158:161], v[166:167], off
	global_load_dwordx4 v[162:165], v[166:167], off offset:256
	s_mov_b64 s[84:85], 0x8000
	s_mov_b64 s[86:87], 0x28000
	v_lshl_add_u64 v[232:233], v[166:167], 0, s[84:85]
	global_load_dwordx4 v[176:179], v[232:233], off
	global_load_dwordx4 v[180:183], v[232:233], off offset:256
	v_lshl_add_u64 v[232:233], v[232:233], 0, s[84:85]
	global_load_dwordx4 v[184:187], v[232:233], off
	global_load_dwordx4 v[188:191], v[232:233], off offset:256
	v_lshl_add_u64 v[232:233], v[232:233], 0, s[84:85]
	global_load_dwordx4 v[192:195], v[232:233], off
	global_load_dwordx4 v[196:199], v[232:233], off offset:256
	v_lshl_add_u64 v[232:233], v[232:233], 0, s[86:87]
	global_load_dwordx4 v[200:203], v[232:233], off
	global_load_dwordx4 v[204:207], v[232:233], off offset:256
	v_lshl_add_u64 v[232:233], v[232:233], 0, s[84:85]
	global_load_dwordx4 v[208:211], v[232:233], off
	global_load_dwordx4 v[212:215], v[232:233], off offset:256
	v_lshl_add_u64 v[232:233], v[232:233], 0, s[84:85]
	global_load_dwordx4 v[216:219], v[232:233], off
	global_load_dwordx4 v[220:223], v[232:233], off offset:256
	v_lshl_add_u64 v[232:233], v[232:233], 0, s[84:85]
	global_load_dwordx4 v[224:227], v[232:233], off
	global_load_dwordx4 v[228:231], v[232:233], off offset:256
	s_cmpk_gt_u32 s35, 0xff
	s_cbranch_scc1 .Lg248_nox
	s_barrier
	s_setprio 1

.Lg359_noy:
	ds_read_b128 v[128:131], v181
	ds_read_b128 v[132:135], v181 offset:1024
	ds_read_b128 v[136:139], v181 offset:2048
	ds_read_b128 v[166:169], v181 offset:3072
	s_add_u32 s38, s8, 0xfffc0080
	s_addc_u32 s39, s9, -1
	s_cmp_eq_u32 s75, 12
	s_cselect_b32 s41, s21, s39
	s_cselect_b32 s40, s71, s38
	s_cselect_b32 s39, s19, s74
	s_cselect_b32 s38, s72, s73
	s_add_i32 m0, s37, 0xc000
	ds_read_b128 v[170:173], v182
	ds_read_b128 v[174:177], v182 offset:1024
	ds_read_b128 v[192:195], v182 offset:2048
	ds_read_b128 v[196:199], v182 offset:3072
	ds_read_b128 v[200:203], v182 offset:4096
	ds_read_b128 v[204:207], v182 offset:5120
	ds_read_b128 v[208:211], v182 offset:6144
	ds_read_b128 v[212:215], v182 offset:7168
	global_load_lds_dwordx4 v158, s[8:9]
	s_add_i32 m0, s37, 0xe000
	s_nop 0
	global_load_lds_dwordx4 v160, s[8:9]
	s_waitcnt lgkmcnt(8)
	s_barrier
	s_waitcnt lgkmcnt(0)
	s_waitcnt lgkmcnt(0)
	v_mfma_f32_16x16x32_bf16 v[124:127], v[128:131], v[170:173], 0
	ds_read_b128 v[216:219], v183
	v_mfma_f32_16x16x32_bf16 v[116:119], v[136:139], v[170:173], 0
	v_mfma_f32_16x16x32_bf16 v[108:111], v[128:131], v[192:195], 0
	ds_read_b128 v[220:223], v183 offset:1024
	v_mfma_f32_16x16x32_bf16 v[100:103], v[136:139], v[192:195], 0
	v_mfma_f32_16x16x32_bf16 v[92:95], v[128:131], v[200:203], 0
	ds_read_b128 v[224:227], v183 offset:2048
	v_mfma_f32_16x16x32_bf16 v[84:87], v[136:139], v[200:203], 0
	v_mfma_f32_16x16x32_bf16 v[76:79], v[128:131], v[208:211], 0
	ds_read_b128 v[228:231], v183 offset:3072
	v_mfma_f32_16x16x32_bf16 v[68:71], v[136:139], v[208:211], 0
	v_mfma_f32_16x16x32_bf16 v[124:127], v[132:135], v[174:177], v[124:127]
	v_mfma_f32_16x16x32_bf16 v[116:119], v[166:169], v[174:177], v[116:119]
	v_mfma_f32_16x16x32_bf16 v[108:111], v[132:135], v[196:199], v[108:111]
	v_mfma_f32_16x16x32_bf16 v[100:103], v[166:169], v[196:199], v[100:103]
	v_mfma_f32_16x16x32_bf16 v[92:95], v[132:135], v[204:207], v[92:95]
	v_mfma_f32_16x16x32_bf16 v[84:87], v[166:169], v[204:207], v[84:87]
	v_mfma_f32_16x16x32_bf16 v[76:79], v[132:135], v[212:215], v[76:79]
	v_mfma_f32_16x16x32_bf16 v[68:71], v[166:169], v[212:215], v[68:71]
	s_barrier
	s_add_i32 s76, s63, s46
	s_add_u32 s80, s38, 0x80
	s_addc_u32 s81, s39, 0
	s_mov_b32 m0, s76
	global_load_lds_dwordx4 v144, s[38:39]
	s_add_i32 m0, s76, 0x2000
	s_nop 0
	global_load_lds_dwordx4 v148, s[38:39]
	s_waitcnt vmcnt(10)
	s_barrier
	s_waitcnt lgkmcnt(0)
	s_waitcnt lgkmcnt(0)
	v_mfma_f32_16x16x32_bf16 v[120:123], v[216:219], v[170:173], 0
	v_mfma_f32_16x16x32_bf16 v[112:115], v[224:227], v[170:173], 0
	v_mfma_f32_16x16x32_bf16 v[104:107], v[216:219], v[192:195], 0
	v_mfma_f32_16x16x32_bf16 v[96:99], v[224:227], v[192:195], 0
	v_mfma_f32_16x16x32_bf16 v[88:91], v[216:219], v[200:203], 0
	v_mfma_f32_16x16x32_bf16 v[80:83], v[224:227], v[200:203], 0
	v_mfma_f32_16x16x32_bf16 v[72:75], v[216:219], v[208:211], 0
	v_mfma_f32_16x16x32_bf16 v[64:67], v[224:227], v[208:211], 0
	v_mfma_f32_16x16x32_bf16 v[120:123], v[220:223], v[174:177], v[120:123]
	v_mfma_f32_16x16x32_bf16 v[112:115], v[228:231], v[174:177], v[112:115]
	v_mfma_f32_16x16x32_bf16 v[104:107], v[220:223], v[196:199], v[104:107]
	v_mfma_f32_16x16x32_bf16 v[96:99], v[228:231], v[196:199], v[96:99]
	v_mfma_f32_16x16x32_bf16 v[88:91], v[220:223], v[204:207], v[88:91]
	v_mfma_f32_16x16x32_bf16 v[80:83], v[228:231], v[204:207], v[80:83]
	v_mfma_f32_16x16x32_bf16 v[72:75], v[220:223], v[212:215], v[72:75]
	v_mfma_f32_16x16x32_bf16 v[64:67], v[228:231], v[212:215], v[64:67]
	s_mov_b32 m0, s37
	s_add_u32 s82, s40, 0x80
	s_addc_u32 s83, s41, 0
	s_barrier
	ds_read_b128 v[170:173], v182 offset:16384
	ds_read_b128 v[174:177], v182 offset:17408
	ds_read_b128 v[192:195], v182 offset:18432
	ds_read_b128 v[196:199], v182 offset:19456
	ds_read_b128 v[200:203], v182 offset:20480
	ds_read_b128 v[204:207], v182 offset:21504
	ds_read_b128 v[208:211], v182 offset:22528
	ds_read_b128 v[212:215], v182 offset:23552
	global_load_lds_dwordx4 v142, s[40:41]
	s_mov_b32 m0, s51
	s_nop 0
	global_load_lds_dwordx4 v146, s[40:41]
	s_barrier
	s_waitcnt lgkmcnt(0)
	s_waitcnt lgkmcnt(0)
	v_mfma_f32_16x16x32_bf16 v[60:63], v[128:131], v[170:173], 0
	v_mfma_f32_16x16x32_bf16 v[52:55], v[136:139], v[170:173], 0
	v_mfma_f32_16x16x32_bf16 v[44:47], v[128:131], v[192:195], 0
	v_mfma_f32_16x16x32_bf16 v[36:39], v[136:139], v[192:195], 0
	v_mfma_f32_16x16x32_bf16 v[28:31], v[128:131], v[200:203], 0
	v_mfma_f32_16x16x32_bf16 v[20:23], v[136:139], v[200:203], 0
	v_mfma_f32_16x16x32_bf16 v[12:15], v[128:131], v[208:211], 0
	v_mfma_f32_16x16x32_bf16 v[4:7], v[136:139], v[208:211], 0
	v_mfma_f32_16x16x32_bf16 v[60:63], v[132:135], v[174:177], v[60:63]
	v_mfma_f32_16x16x32_bf16 v[52:55], v[166:169], v[174:177], v[52:55]
	v_mfma_f32_16x16x32_bf16 v[44:47], v[132:135], v[196:199], v[44:47]
	v_mfma_f32_16x16x32_bf16 v[36:39], v[166:169], v[196:199], v[36:39]
	v_mfma_f32_16x16x32_bf16 v[28:31], v[132:135], v[204:207], v[28:31]
	v_mfma_f32_16x16x32_bf16 v[20:23], v[166:169], v[204:207], v[20:23]
	v_mfma_f32_16x16x32_bf16 v[12:15], v[132:135], v[212:215], v[12:15]
	v_mfma_f32_16x16x32_bf16 v[4:7], v[166:169], v[212:215], v[4:7]
	s_barrier
	s_add_u32 s76, s38, 0x40000
	s_addc_u32 s77, s39, 0
	s_add_i32 s78, s64, s46
	s_mov_b32 m0, s78
	s_nop 0
	global_load_lds_dwordx4 v144, s[76:77]
	s_add_i32 m0, s78, 0x2000
	s_nop 0
	global_load_lds_dwordx4 v148, s[76:77]
	s_waitcnt vmcnt(8)
	s_barrier
	v_mfma_f32_16x16x32_bf16 v[56:59], v[216:219], v[170:173], 0
	v_mfma_f32_16x16x32_bf16 v[48:51], v[224:227], v[170:173], 0
	v_mfma_f32_16x16x32_bf16 v[40:43], v[216:219], v[192:195], 0
	v_mfma_f32_16x16x32_bf16 v[32:35], v[224:227], v[192:195], 0
	v_mfma_f32_16x16x32_bf16 v[24:27], v[216:219], v[200:203], 0
	v_mfma_f32_16x16x32_bf16 v[16:19], v[224:227], v[200:203], 0
	v_mfma_f32_16x16x32_bf16 v[8:11], v[216:219], v[208:211], 0
	v_mfma_f32_16x16x32_bf16 v[0:3], v[224:227], v[208:211], 0
	v_mfma_f32_16x16x32_bf16 v[56:59], v[220:223], v[174:177], v[56:59]
	v_mfma_f32_16x16x32_bf16 v[48:51], v[228:231], v[174:177], v[48:51]
	v_mfma_f32_16x16x32_bf16 v[40:43], v[220:223], v[196:199], v[40:43]
	v_mfma_f32_16x16x32_bf16 v[32:35], v[228:231], v[196:199], v[32:35]
	v_mfma_f32_16x16x32_bf16 v[24:27], v[220:223], v[204:207], v[24:27]
	v_mfma_f32_16x16x32_bf16 v[16:19], v[228:231], v[204:207], v[16:19]
	v_mfma_f32_16x16x32_bf16 v[8:11], v[220:223], v[212:215], v[8:11]
	v_mfma_f32_16x16x32_bf16 v[0:3], v[228:231], v[212:215], v[0:3]
	s_add_i32 s76, 0, 0x18000
	v_add_u32_e32 v150, s76, v179
	s_barrier
	s_branch .Lg359_mid
.LBB0_359:
	ds_read_b128 v[128:131], v181
	ds_read_b128 v[132:135], v181 offset:1024
	ds_read_b128 v[136:139], v181 offset:2048
	ds_read_b128 v[166:169], v181 offset:3072
	s_add_u32 s38, s8, 0xfffc0080
	s_addc_u32 s39, s9, -1
	s_cmp_eq_u32 s75, 12
	s_cselect_b32 s41, s21, s39
	s_cselect_b32 s40, s71, s38
	s_cselect_b32 s39, s19, s74
	s_cselect_b32 s38, s72, s73
	s_add_i32 m0, s37, 0xc000
	ds_read_b128 v[170:173], v182
	ds_read_b128 v[174:177], v182 offset:1024
	ds_read_b128 v[192:195], v182 offset:2048
	ds_read_b128 v[196:199], v182 offset:3072
	ds_read_b128 v[200:203], v182 offset:4096
	ds_read_b128 v[204:207], v182 offset:5120
	ds_read_b128 v[208:211], v182 offset:6144
	ds_read_b128 v[212:215], v182 offset:7168
	global_load_lds_dwordx4 v158, s[8:9]
	s_add_i32 m0, s37, 0xe000
	s_nop 0
	global_load_lds_dwordx4 v160, s[8:9]
	s_waitcnt lgkmcnt(8)
	s_barrier
	s_waitcnt lgkmcnt(0)
	s_waitcnt lgkmcnt(0)
	v_mfma_f32_16x16x32_bf16 v[124:127], v[128:131], v[170:173], v[124:127]
	ds_read_b128 v[216:219], v183
	v_mfma_f32_16x16x32_bf16 v[116:119], v[136:139], v[170:173], v[116:119]
	v_mfma_f32_16x16x32_bf16 v[108:111], v[128:131], v[192:195], v[108:111]
	ds_read_b128 v[220:223], v183 offset:1024
	v_mfma_f32_16x16x32_bf16 v[100:103], v[136:139], v[192:195], v[100:103]
	v_mfma_f32_16x16x32_bf16 v[92:95], v[128:131], v[200:203], v[92:95]
	ds_read_b128 v[224:227], v183 offset:2048
	v_mfma_f32_16x16x32_bf16 v[84:87], v[136:139], v[200:203], v[84:87]
	v_mfma_f32_16x16x32_bf16 v[76:79], v[128:131], v[208:211], v[76:79]
	ds_read_b128 v[228:231], v183 offset:3072
	v_mfma_f32_16x16x32_bf16 v[68:71], v[136:139], v[208:211], v[68:71]
	v_mfma_f32_16x16x32_bf16 v[124:127], v[132:135], v[174:177], v[124:127]
	v_mfma_f32_16x16x32_bf16 v[116:119], v[166:169], v[174:177], v[116:119]
	v_mfma_f32_16x16x32_bf16 v[108:111], v[132:135], v[196:199], v[108:111]
	v_mfma_f32_16x16x32_bf16 v[100:103], v[166:169], v[196:199], v[100:103]
	v_mfma_f32_16x16x32_bf16 v[92:95], v[132:135], v[204:207], v[92:95]
	v_mfma_f32_16x16x32_bf16 v[84:87], v[166:169], v[204:207], v[84:87]
	v_mfma_f32_16x16x32_bf16 v[76:79], v[132:135], v[212:215], v[76:79]
	v_mfma_f32_16x16x32_bf16 v[68:71], v[166:169], v[212:215], v[68:71]
	s_barrier
	s_add_i32 s76, s63, s46
	s_add_u32 s80, s38, 0x80
	s_addc_u32 s81, s39, 0
	s_mov_b32 m0, s76
	global_load_lds_dwordx4 v144, s[38:39]
	s_add_i32 m0, s76, 0x2000
	s_nop 0
	global_load_lds_dwordx4 v148, s[38:39]
	s_waitcnt vmcnt(10)
	s_barrier
	s_waitcnt lgkmcnt(0)
	s_waitcnt lgkmcnt(0)
	v_mfma_f32_16x16x32_bf16 v[120:123], v[216:219], v[170:173], v[120:123]
	v_mfma_f32_16x16x32_bf16 v[112:115], v[224:227], v[170:173], v[112:115]
	v_mfma_f32_16x16x32_bf16 v[104:107], v[216:219], v[192:195], v[104:107]
	v_mfma_f32_16x16x32_bf16 v[96:99], v[224:227], v[192:195], v[96:99]
	v_mfma_f32_16x16x32_bf16 v[88:91], v[216:219], v[200:203], v[88:91]
	v_mfma_f32_16x16x32_bf16 v[80:83], v[224:227], v[200:203], v[80:83]
	v_mfma_f32_16x16x32_bf16 v[72:75], v[216:219], v[208:211], v[72:75]
	v_mfma_f32_16x16x32_bf16 v[64:67], v[224:227], v[208:211], v[64:67]
	v_mfma_f32_16x16x32_bf16 v[120:123], v[220:223], v[174:177], v[120:123]
	v_mfma_f32_16x16x32_bf16 v[112:115], v[228:231], v[174:177], v[112:115]
	v_mfma_f32_16x16x32_bf16 v[104:107], v[220:223], v[196:199], v[104:107]
	v_mfma_f32_16x16x32_bf16 v[96:99], v[228:231], v[196:199], v[96:99]
	v_mfma_f32_16x16x32_bf16 v[88:91], v[220:223], v[204:207], v[88:91]
	v_mfma_f32_16x16x32_bf16 v[80:83], v[228:231], v[204:207], v[80:83]
	v_mfma_f32_16x16x32_bf16 v[72:75], v[220:223], v[212:215], v[72:75]
	v_mfma_f32_16x16x32_bf16 v[64:67], v[228:231], v[212:215], v[64:67]
	s_mov_b32 m0, s37
	s_add_u32 s82, s40, 0x80
	s_addc_u32 s83, s41, 0
	s_barrier
	ds_read_b128 v[170:173], v182 offset:16384
	ds_read_b128 v[174:177], v182 offset:17408
	ds_read_b128 v[192:195], v182 offset:18432
	ds_read_b128 v[196:199], v182 offset:19456
	ds_read_b128 v[200:203], v182 offset:20480
	ds_read_b128 v[204:207], v182 offset:21504
	ds_read_b128 v[208:211], v182 offset:22528
	ds_read_b128 v[212:215], v182 offset:23552
	global_load_lds_dwordx4 v142, s[40:41]
	s_mov_b32 m0, s51
	s_nop 0
	global_load_lds_dwordx4 v146, s[40:41]
	s_barrier
	s_waitcnt lgkmcnt(0)
	s_waitcnt lgkmcnt(0)
	v_mfma_f32_16x16x32_bf16 v[60:63], v[128:131], v[170:173], v[60:63]
	v_mfma_f32_16x16x32_bf16 v[52:55], v[136:139], v[170:173], v[52:55]
	v_mfma_f32_16x16x32_bf16 v[44:47], v[128:131], v[192:195], v[44:47]
	v_mfma_f32_16x16x32_bf16 v[36:39], v[136:139], v[192:195], v[36:39]
	v_mfma_f32_16x16x32_bf16 v[28:31], v[128:131], v[200:203], v[28:31]
	v_mfma_f32_16x16x32_bf16 v[20:23], v[136:139], v[200:203], v[20:23]
	v_mfma_f32_16x16x32_bf16 v[12:15], v[128:131], v[208:211], v[12:15]
	v_mfma_f32_16x16x32_bf16 v[4:7], v[136:139], v[208:211], v[4:7]
	v_mfma_f32_16x16x32_bf16 v[60:63], v[132:135], v[174:177], v[60:63]
	v_mfma_f32_16x16x32_bf16 v[52:55], v[166:169], v[174:177], v[52:55]
	v_mfma_f32_16x16x32_bf16 v[44:47], v[132:135], v[196:199], v[44:47]
	v_mfma_f32_16x16x32_bf16 v[36:39], v[166:169], v[196:199], v[36:39]
	v_mfma_f32_16x16x32_bf16 v[28:31], v[132:135], v[204:207], v[28:31]
	v_mfma_f32_16x16x32_bf16 v[20:23], v[166:169], v[204:207], v[20:23]
	v_mfma_f32_16x16x32_bf16 v[12:15], v[132:135], v[212:215], v[12:15]
	v_mfma_f32_16x16x32_bf16 v[4:7], v[166:169], v[212:215], v[4:7]
	s_barrier
	s_add_u32 s76, s38, 0x40000
	s_addc_u32 s77, s39, 0
	s_add_i32 s78, s64, s46
	s_mov_b32 m0, s78
	s_nop 0
	global_load_lds_dwordx4 v144, s[76:77]
	s_add_i32 m0, s78, 0x2000
	s_nop 0
	global_load_lds_dwordx4 v148, s[76:77]
	s_waitcnt vmcnt(8)
	s_barrier
	v_mfma_f32_16x16x32_bf16 v[56:59], v[216:219], v[170:173], v[56:59]
	v_mfma_f32_16x16x32_bf16 v[48:51], v[224:227], v[170:173], v[48:51]
	v_mfma_f32_16x16x32_bf16 v[40:43], v[216:219], v[192:195], v[40:43]
	v_mfma_f32_16x16x32_bf16 v[32:35], v[224:227], v[192:195], v[32:35]
	v_mfma_f32_16x16x32_bf16 v[24:27], v[216:219], v[200:203], v[24:27]
	v_mfma_f32_16x16x32_bf16 v[16:19], v[224:227], v[200:203], v[16:19]
	v_mfma_f32_16x16x32_bf16 v[8:11], v[216:219], v[208:211], v[8:11]
	v_mfma_f32_16x16x32_bf16 v[0:3], v[224:227], v[208:211], v[0:3]
	v_mfma_f32_16x16x32_bf16 v[56:59], v[220:223], v[174:177], v[56:59]
	v_mfma_f32_16x16x32_bf16 v[48:51], v[228:231], v[174:177], v[48:51]
	v_mfma_f32_16x16x32_bf16 v[40:43], v[220:223], v[196:199], v[40:43]
	v_mfma_f32_16x16x32_bf16 v[32:35], v[228:231], v[196:199], v[32:35]
	v_mfma_f32_16x16x32_bf16 v[24:27], v[220:223], v[204:207], v[24:27]
	v_mfma_f32_16x16x32_bf16 v[16:19], v[228:231], v[204:207], v[16:19]
	v_mfma_f32_16x16x32_bf16 v[8:11], v[220:223], v[212:215], v[8:11]
	v_mfma_f32_16x16x32_bf16 v[0:3], v[228:231], v[212:215], v[0:3]
	s_add_i32 s76, 0, 0x18000
	v_add_u32_e32 v150, s76, v179
	s_barrier
.Lg359_mid:
	ds_read_b128 v[128:131], v150
	ds_read_b128 v[132:135], v150 offset:1024
	ds_read_b128 v[136:139], v150 offset:2048
	ds_read_b128 v[166:169], v150 offset:3072
	s_add_u32 s40, s40, 0x40000
	s_addc_u32 s41, s41, 0
	s_mov_b32 m0, s52
	ds_read_b128 v[170:173], v182 offset:32768
	ds_read_b128 v[174:177], v182 offset:33792
	ds_read_b128 v[192:195], v182 offset:34816
	ds_read_b128 v[196:199], v182 offset:35840
	ds_read_b128 v[200:203], v182 offset:36864
	ds_read_b128 v[204:207], v182 offset:37888
	ds_read_b128 v[208:211], v182 offset:38912
	ds_read_b128 v[212:215], v182 offset:39936
	global_load_lds_dwordx4 v142, s[40:41]
	s_mov_b32 m0, s53
	s_nop 0
	global_load_lds_dwordx4 v146, s[40:41]
	s_waitcnt lgkmcnt(8)
	s_barrier
	s_waitcnt lgkmcnt(0)
	s_waitcnt lgkmcnt(0)
	s_add_i32 s40, 0, 0x1c000
	v_add_u32_e32 v150, s40, v179
	v_mfma_f32_16x16x32_bf16 v[124:127], v[128:131], v[170:173], v[124:127]
	ds_read_b128 v[216:219], v150
	v_mfma_f32_16x16x32_bf16 v[116:119], v[136:139], v[170:173], v[116:119]
	v_mfma_f32_16x16x32_bf16 v[108:111], v[128:131], v[192:195], v[108:111]
	ds_read_b128 v[220:223], v150 offset:1024
	v_mfma_f32_16x16x32_bf16 v[100:103], v[136:139], v[192:195], v[100:103]
	v_mfma_f32_16x16x32_bf16 v[92:95], v[128:131], v[200:203], v[92:95]
	ds_read_b128 v[224:227], v150 offset:2048
	v_mfma_f32_16x16x32_bf16 v[84:87], v[136:139], v[200:203], v[84:87]
	v_mfma_f32_16x16x32_bf16 v[76:79], v[128:131], v[208:211], v[76:79]
	ds_read_b128 v[228:231], v150 offset:3072
	v_mfma_f32_16x16x32_bf16 v[68:71], v[136:139], v[208:211], v[68:71]
	v_mfma_f32_16x16x32_bf16 v[124:127], v[132:135], v[174:177], v[124:127]
	v_mfma_f32_16x16x32_bf16 v[116:119], v[166:169], v[174:177], v[116:119]
	v_mfma_f32_16x16x32_bf16 v[108:111], v[132:135], v[196:199], v[108:111]
	v_mfma_f32_16x16x32_bf16 v[100:103], v[166:169], v[196:199], v[100:103]
	v_mfma_f32_16x16x32_bf16 v[92:95], v[132:135], v[204:207], v[92:95]
	v_mfma_f32_16x16x32_bf16 v[84:87], v[166:169], v[204:207], v[84:87]
	v_mfma_f32_16x16x32_bf16 v[76:79], v[132:135], v[212:215], v[76:79]
	v_mfma_f32_16x16x32_bf16 v[68:71], v[166:169], v[212:215], v[68:71]
	s_barrier
	s_add_i32 s41, s76, s46
	s_mov_b32 m0, s41
	global_load_lds_dwordx4 v144, s[80:81]
	s_add_i32 m0, s41, 0x2000
	s_nop 0
	global_load_lds_dwordx4 v148, s[80:81]
	s_waitcnt vmcnt(10)
	s_barrier
	s_waitcnt lgkmcnt(0)
	s_waitcnt lgkmcnt(0)
	v_mfma_f32_16x16x32_bf16 v[120:123], v[216:219], v[170:173], v[120:123]
	v_mfma_f32_16x16x32_bf16 v[112:115], v[224:227], v[170:173], v[112:115]
	v_mfma_f32_16x16x32_bf16 v[104:107], v[216:219], v[192:195], v[104:107]
	v_mfma_f32_16x16x32_bf16 v[96:99], v[224:227], v[192:195], v[96:99]
	v_mfma_f32_16x16x32_bf16 v[88:91], v[216:219], v[200:203], v[88:91]
	v_mfma_f32_16x16x32_bf16 v[80:83], v[224:227], v[200:203], v[80:83]
	v_mfma_f32_16x16x32_bf16 v[72:75], v[216:219], v[208:211], v[72:75]
	v_mfma_f32_16x16x32_bf16 v[64:67], v[224:227], v[208:211], v[64:67]
	v_mfma_f32_16x16x32_bf16 v[120:123], v[220:223], v[174:177], v[120:123]
	v_mfma_f32_16x16x32_bf16 v[112:115], v[228:231], v[174:177], v[112:115]
	v_mfma_f32_16x16x32_bf16 v[104:107], v[220:223], v[196:199], v[104:107]
	v_mfma_f32_16x16x32_bf16 v[96:99], v[228:231], v[196:199], v[96:99]
	v_mfma_f32_16x16x32_bf16 v[88:91], v[220:223], v[204:207], v[88:91]
	v_mfma_f32_16x16x32_bf16 v[80:83], v[228:231], v[204:207], v[80:83]
	v_mfma_f32_16x16x32_bf16 v[72:75], v[220:223], v[212:215], v[72:75]
	v_mfma_f32_16x16x32_bf16 v[64:67], v[228:231], v[212:215], v[64:67]
	s_mov_b32 m0, s55
	s_barrier
	ds_read_b128 v[170:173], v182 offset:49152
	ds_read_b128 v[174:177], v182 offset:50176
	ds_read_b128 v[192:195], v182 offset:51200
	ds_read_b128 v[196:199], v182 offset:52224
	ds_read_b128 v[200:203], v182 offset:53248
	ds_read_b128 v[204:207], v182 offset:54272
	ds_read_b128 v[208:211], v182 offset:55296
	ds_read_b128 v[212:215], v182 offset:56320
	global_load_lds_dwordx4 v142, s[82:83]
	s_mov_b32 m0, s56
	s_nop 0
	global_load_lds_dwordx4 v146, s[82:83]
	s_barrier
	s_waitcnt lgkmcnt(0)
	s_waitcnt lgkmcnt(0)
	v_mfma_f32_16x16x32_bf16 v[60:63], v[128:131], v[170:173], v[60:63]
	v_mfma_f32_16x16x32_bf16 v[52:55], v[136:139], v[170:173], v[52:55]
	v_mfma_f32_16x16x32_bf16 v[44:47], v[128:131], v[192:195], v[44:47]
	v_mfma_f32_16x16x32_bf16 v[36:39], v[136:139], v[192:195], v[36:39]
	v_mfma_f32_16x16x32_bf16 v[28:31], v[128:131], v[200:203], v[28:31]
	v_mfma_f32_16x16x32_bf16 v[20:23], v[136:139], v[200:203], v[20:23]
	v_mfma_f32_16x16x32_bf16 v[12:15], v[128:131], v[208:211], v[12:15]
	v_mfma_f32_16x16x32_bf16 v[4:7], v[136:139], v[208:211], v[4:7]
	v_mfma_f32_16x16x32_bf16 v[60:63], v[132:135], v[174:177], v[60:63]
	v_mfma_f32_16x16x32_bf16 v[52:55], v[166:169], v[174:177], v[52:55]
	v_mfma_f32_16x16x32_bf16 v[44:47], v[132:135], v[196:199], v[44:47]
	v_mfma_f32_16x16x32_bf16 v[36:39], v[166:169], v[196:199], v[36:39]
	v_mfma_f32_16x16x32_bf16 v[28:31], v[132:135], v[204:207], v[28:31]
	v_mfma_f32_16x16x32_bf16 v[20:23], v[166:169], v[204:207], v[20:23]
	v_mfma_f32_16x16x32_bf16 v[12:15], v[132:135], v[212:215], v[12:15]
	v_mfma_f32_16x16x32_bf16 v[4:7], v[166:169], v[212:215], v[4:7]
	s_barrier
	s_add_u32 s38, s38, 0x40080
	s_addc_u32 s39, s39, 0
	s_add_i32 s40, s40, s46
	s_mov_b32 m0, s40
	s_nop 0
	global_load_lds_dwordx4 v144, s[38:39]
	s_add_i32 m0, s40, 0x2000
	s_nop 0
	global_load_lds_dwordx4 v148, s[38:39]
	s_waitcnt vmcnt(8)
	s_barrier
	v_mfma_f32_16x16x32_bf16 v[56:59], v[216:219], v[170:173], v[56:59]
	v_mfma_f32_16x16x32_bf16 v[48:51], v[224:227], v[170:173], v[48:51]
	v_mfma_f32_16x16x32_bf16 v[40:43], v[216:219], v[192:195], v[40:43]
	v_mfma_f32_16x16x32_bf16 v[32:35], v[224:227], v[192:195], v[32:35]
	v_mfma_f32_16x16x32_bf16 v[24:27], v[216:219], v[200:203], v[24:27]
	v_mfma_f32_16x16x32_bf16 v[16:19], v[224:227], v[200:203], v[16:19]
	v_mfma_f32_16x16x32_bf16 v[8:11], v[216:219], v[208:211], v[8:11]
	v_mfma_f32_16x16x32_bf16 v[0:3], v[224:227], v[208:211], v[0:3]
	v_mfma_f32_16x16x32_bf16 v[56:59], v[220:223], v[174:177], v[56:59]
	v_mfma_f32_16x16x32_bf16 v[48:51], v[228:231], v[174:177], v[48:51]
	v_mfma_f32_16x16x32_bf16 v[40:43], v[220:223], v[196:199], v[40:43]
	v_mfma_f32_16x16x32_bf16 v[32:35], v[228:231], v[196:199], v[32:35]
	v_mfma_f32_16x16x32_bf16 v[24:27], v[220:223], v[204:207], v[24:27]
	v_mfma_f32_16x16x32_bf16 v[16:19], v[228:231], v[204:207], v[16:19]
	v_mfma_f32_16x16x32_bf16 v[8:11], v[220:223], v[212:215], v[8:11]
	v_mfma_f32_16x16x32_bf16 v[0:3], v[228:231], v[212:215], v[0:3]
	s_add_i32 s75, s75, 2
	s_add_u32 s8, s8, 0x100
	s_addc_u32 s9, s9, 0
	s_add_u32 s73, s73, 0x100
	s_addc_u32 s74, s74, 0
	s_cmp_gt_u32 s75, 13
	s_barrier
	s_cbranch_scc0 .LBB0_359
	s_setprio 0
	s_cmpk_gt_u32 s45, 0xff
	s_cbranch_scc1 .Lg359_nox
	s_barrier
	s_setprio 1

.Lg786_noy:
	ds_read_b128 v[144:147], v151
	ds_read_b128 v[156:159], v151 offset:1024
	ds_read_b128 v[160:163], v151 offset:2048
	ds_read_b128 v[164:167], v151 offset:3072
	s_add_u32 s30, s28, 0xfffc0080
	s_addc_u32 s31, s29, -1
	s_cmp_eq_u32 s61, 12
	s_cselect_b32 s35, s19, s31
	s_cselect_b32 s34, s57, s30
	s_cselect_b32 s31, s17, s60
	s_cselect_b32 s30, s58, s59
	s_add_i32 m0, s45, 0xc000
	ds_read_b128 v[168:171], v152
	ds_read_b128 v[172:175], v152 offset:1024
	ds_read_b128 v[176:179], v152 offset:2048
	ds_read_b128 v[180:183], v152 offset:3072
	ds_read_b128 v[184:187], v152 offset:4096
	ds_read_b128 v[188:191], v152 offset:5120
	ds_read_b128 v[192:195], v152 offset:6144
	ds_read_b128 v[196:199], v152 offset:7168
	global_load_lds_dwordx4 v136, s[28:29]
	s_add_i32 m0, s45, 0xe000
	s_nop 0
	global_load_lds_dwordx4 v138, s[28:29]
	s_waitcnt lgkmcnt(8)
	s_barrier
	s_waitcnt lgkmcnt(0)
	s_waitcnt lgkmcnt(0)
	v_mfma_f32_16x16x32_bf16 v[124:127], v[144:147], v[168:171], 0
	ds_read_b128 v[200:203], v153
	v_mfma_f32_16x16x32_bf16 v[120:123], v[160:163], v[168:171], 0
	v_mfma_f32_16x16x32_bf16 v[108:111], v[144:147], v[176:179], 0
	ds_read_b128 v[204:207], v153 offset:1024
	v_mfma_f32_16x16x32_bf16 v[104:107], v[160:163], v[176:179], 0
	v_mfma_f32_16x16x32_bf16 v[92:95], v[144:147], v[184:187], 0
	ds_read_b128 v[208:211], v153 offset:2048
	v_mfma_f32_16x16x32_bf16 v[88:91], v[160:163], v[184:187], 0
	v_mfma_f32_16x16x32_bf16 v[76:79], v[144:147], v[192:195], 0
	ds_read_b128 v[212:215], v153 offset:3072
	v_mfma_f32_16x16x32_bf16 v[72:75], v[160:163], v[192:195], 0
	v_mfma_f32_16x16x32_bf16 v[124:127], v[156:159], v[172:175], v[124:127]
	v_mfma_f32_16x16x32_bf16 v[120:123], v[164:167], v[172:175], v[120:123]
	v_mfma_f32_16x16x32_bf16 v[108:111], v[156:159], v[180:183], v[108:111]
	v_mfma_f32_16x16x32_bf16 v[104:107], v[164:167], v[180:183], v[104:107]
	v_mfma_f32_16x16x32_bf16 v[92:95], v[156:159], v[188:191], v[92:95]
	v_mfma_f32_16x16x32_bf16 v[88:91], v[164:167], v[188:191], v[88:91]
	v_mfma_f32_16x16x32_bf16 v[76:79], v[156:159], v[196:199], v[76:79]
	v_mfma_f32_16x16x32_bf16 v[72:75], v[164:167], v[196:199], v[72:75]
	s_barrier
	s_add_i32 s62, s53, s42
	s_add_u32 s80, s30, 0x80
	s_addc_u32 s81, s31, 0
	s_mov_b32 m0, s62
	global_load_lds_dwordx4 v132, s[30:31]
	s_add_i32 m0, s62, 0x2000
	s_nop 0
	global_load_lds_dwordx4 v128, s[30:31]
	s_waitcnt vmcnt(10)
	s_barrier
	s_waitcnt lgkmcnt(0)
	s_waitcnt lgkmcnt(0)
	v_mfma_f32_16x16x32_bf16 v[116:119], v[200:203], v[168:171], 0
	v_mfma_f32_16x16x32_bf16 v[112:115], v[208:211], v[168:171], 0
	v_mfma_f32_16x16x32_bf16 v[100:103], v[200:203], v[176:179], 0
	v_mfma_f32_16x16x32_bf16 v[96:99], v[208:211], v[176:179], 0
	v_mfma_f32_16x16x32_bf16 v[84:87], v[200:203], v[184:187], 0
	v_mfma_f32_16x16x32_bf16 v[80:83], v[208:211], v[184:187], 0
	v_mfma_f32_16x16x32_bf16 v[68:71], v[200:203], v[192:195], 0
	v_mfma_f32_16x16x32_bf16 v[64:67], v[208:211], v[192:195], 0
	v_mfma_f32_16x16x32_bf16 v[116:119], v[204:207], v[172:175], v[116:119]
	v_mfma_f32_16x16x32_bf16 v[112:115], v[212:215], v[172:175], v[112:115]
	v_mfma_f32_16x16x32_bf16 v[100:103], v[204:207], v[180:183], v[100:103]
	v_mfma_f32_16x16x32_bf16 v[96:99], v[212:215], v[180:183], v[96:99]
	v_mfma_f32_16x16x32_bf16 v[84:87], v[204:207], v[188:191], v[84:87]
	v_mfma_f32_16x16x32_bf16 v[80:83], v[212:215], v[188:191], v[80:83]
	v_mfma_f32_16x16x32_bf16 v[68:71], v[204:207], v[196:199], v[68:71]
	v_mfma_f32_16x16x32_bf16 v[64:67], v[212:215], v[196:199], v[64:67]
	s_mov_b32 m0, s45
	s_add_u32 s82, s34, 0x80
	s_addc_u32 s83, s35, 0
	s_barrier
	ds_read_b128 v[168:171], v152 offset:16384
	ds_read_b128 v[172:175], v152 offset:17408
	ds_read_b128 v[176:179], v152 offset:18432
	ds_read_b128 v[180:183], v152 offset:19456
	ds_read_b128 v[184:187], v152 offset:20480
	ds_read_b128 v[188:191], v152 offset:21504
	ds_read_b128 v[192:195], v152 offset:22528
	ds_read_b128 v[196:199], v152 offset:23552
	global_load_lds_dwordx4 v134, s[34:35]
	s_mov_b32 m0, s46
	s_nop 0
	global_load_lds_dwordx4 v130, s[34:35]
	s_barrier
	s_waitcnt lgkmcnt(0)
	s_waitcnt lgkmcnt(0)
	v_mfma_f32_16x16x32_bf16 v[60:63], v[144:147], v[168:171], 0
	v_mfma_f32_16x16x32_bf16 v[56:59], v[160:163], v[168:171], 0
	v_mfma_f32_16x16x32_bf16 v[44:47], v[144:147], v[176:179], 0
	v_mfma_f32_16x16x32_bf16 v[40:43], v[160:163], v[176:179], 0
	v_mfma_f32_16x16x32_bf16 v[28:31], v[144:147], v[184:187], 0
	v_mfma_f32_16x16x32_bf16 v[24:27], v[160:163], v[184:187], 0
	v_mfma_f32_16x16x32_bf16 v[12:15], v[144:147], v[192:195], 0
	v_mfma_f32_16x16x32_bf16 v[8:11], v[160:163], v[192:195], 0
	v_mfma_f32_16x16x32_bf16 v[60:63], v[156:159], v[172:175], v[60:63]
	v_mfma_f32_16x16x32_bf16 v[56:59], v[164:167], v[172:175], v[56:59]
	v_mfma_f32_16x16x32_bf16 v[44:47], v[156:159], v[180:183], v[44:47]
	v_mfma_f32_16x16x32_bf16 v[40:43], v[164:167], v[180:183], v[40:43]
	v_mfma_f32_16x16x32_bf16 v[28:31], v[156:159], v[188:191], v[28:31]
	v_mfma_f32_16x16x32_bf16 v[24:27], v[164:167], v[188:191], v[24:27]
	v_mfma_f32_16x16x32_bf16 v[12:15], v[156:159], v[196:199], v[12:15]
	v_mfma_f32_16x16x32_bf16 v[8:11], v[164:167], v[196:199], v[8:11]
	s_barrier
	s_add_u32 s62, s30, 0x40000
	s_addc_u32 s63, s31, 0
	s_add_i32 s64, s54, s42
	s_mov_b32 m0, s64
	s_nop 0
	global_load_lds_dwordx4 v132, s[62:63]
	s_add_i32 m0, s64, 0x2000
	s_nop 0
	global_load_lds_dwordx4 v128, s[62:63]
	s_waitcnt vmcnt(8)
	s_barrier
	v_mfma_f32_16x16x32_bf16 v[52:55], v[200:203], v[168:171], 0
	v_mfma_f32_16x16x32_bf16 v[48:51], v[208:211], v[168:171], 0
	v_mfma_f32_16x16x32_bf16 v[36:39], v[200:203], v[176:179], 0
	v_mfma_f32_16x16x32_bf16 v[32:35], v[208:211], v[176:179], 0
	v_mfma_f32_16x16x32_bf16 v[20:23], v[200:203], v[184:187], 0
	v_mfma_f32_16x16x32_bf16 v[16:19], v[208:211], v[184:187], 0
	v_mfma_f32_16x16x32_bf16 v[4:7], v[200:203], v[192:195], 0
	v_mfma_f32_16x16x32_bf16 v[0:3], v[208:211], v[192:195], 0
	v_mfma_f32_16x16x32_bf16 v[52:55], v[204:207], v[172:175], v[52:55]
	v_mfma_f32_16x16x32_bf16 v[48:51], v[212:215], v[172:175], v[48:51]
	v_mfma_f32_16x16x32_bf16 v[36:39], v[204:207], v[180:183], v[36:39]
	v_mfma_f32_16x16x32_bf16 v[32:35], v[212:215], v[180:183], v[32:35]
	v_mfma_f32_16x16x32_bf16 v[20:23], v[204:207], v[188:191], v[20:23]
	v_mfma_f32_16x16x32_bf16 v[16:19], v[212:215], v[188:191], v[16:19]
	v_mfma_f32_16x16x32_bf16 v[4:7], v[204:207], v[196:199], v[4:7]
	v_mfma_f32_16x16x32_bf16 v[0:3], v[212:215], v[196:199], v[0:3]
	s_add_i32 s62, 0, 0x18000
	v_add_u32_e32 v155, s62, v149
	s_barrier
	s_branch .Lg786_mid
.LBB0_786:
	ds_read_b128 v[144:147], v151
	ds_read_b128 v[156:159], v151 offset:1024
	ds_read_b128 v[160:163], v151 offset:2048
	ds_read_b128 v[164:167], v151 offset:3072
	s_add_u32 s30, s28, 0xfffc0080
	s_addc_u32 s31, s29, -1
	s_cmp_eq_u32 s61, 12
	s_cselect_b32 s35, s19, s31
	s_cselect_b32 s34, s57, s30
	s_cselect_b32 s31, s17, s60
	s_cselect_b32 s30, s58, s59
	s_add_i32 m0, s45, 0xc000
	ds_read_b128 v[168:171], v152
	ds_read_b128 v[172:175], v152 offset:1024
	ds_read_b128 v[176:179], v152 offset:2048
	ds_read_b128 v[180:183], v152 offset:3072
	ds_read_b128 v[184:187], v152 offset:4096
	ds_read_b128 v[188:191], v152 offset:5120
	ds_read_b128 v[192:195], v152 offset:6144
	ds_read_b128 v[196:199], v152 offset:7168
	global_load_lds_dwordx4 v136, s[28:29]
	s_add_i32 m0, s45, 0xe000
	s_nop 0
	global_load_lds_dwordx4 v138, s[28:29]
	s_waitcnt lgkmcnt(8)
	s_barrier
	s_waitcnt lgkmcnt(0)
	s_waitcnt lgkmcnt(0)
	v_mfma_f32_16x16x32_bf16 v[124:127], v[144:147], v[168:171], v[124:127]
	ds_read_b128 v[200:203], v153
	v_mfma_f32_16x16x32_bf16 v[120:123], v[160:163], v[168:171], v[120:123]
	v_mfma_f32_16x16x32_bf16 v[108:111], v[144:147], v[176:179], v[108:111]
	ds_read_b128 v[204:207], v153 offset:1024
	v_mfma_f32_16x16x32_bf16 v[104:107], v[160:163], v[176:179], v[104:107]
	v_mfma_f32_16x16x32_bf16 v[92:95], v[144:147], v[184:187], v[92:95]
	ds_read_b128 v[208:211], v153 offset:2048
	v_mfma_f32_16x16x32_bf16 v[88:91], v[160:163], v[184:187], v[88:91]
	v_mfma_f32_16x16x32_bf16 v[76:79], v[144:147], v[192:195], v[76:79]
	ds_read_b128 v[212:215], v153 offset:3072
	v_mfma_f32_16x16x32_bf16 v[72:75], v[160:163], v[192:195], v[72:75]
	v_mfma_f32_16x16x32_bf16 v[124:127], v[156:159], v[172:175], v[124:127]
	v_mfma_f32_16x16x32_bf16 v[120:123], v[164:167], v[172:175], v[120:123]
	v_mfma_f32_16x16x32_bf16 v[108:111], v[156:159], v[180:183], v[108:111]
	v_mfma_f32_16x16x32_bf16 v[104:107], v[164:167], v[180:183], v[104:107]
	v_mfma_f32_16x16x32_bf16 v[92:95], v[156:159], v[188:191], v[92:95]
	v_mfma_f32_16x16x32_bf16 v[88:91], v[164:167], v[188:191], v[88:91]
	v_mfma_f32_16x16x32_bf16 v[76:79], v[156:159], v[196:199], v[76:79]
	v_mfma_f32_16x16x32_bf16 v[72:75], v[164:167], v[196:199], v[72:75]
	s_barrier
	s_add_i32 s62, s53, s42
	s_add_u32 s80, s30, 0x80
	s_addc_u32 s81, s31, 0
	s_mov_b32 m0, s62
	global_load_lds_dwordx4 v132, s[30:31]
	s_add_i32 m0, s62, 0x2000
	s_nop 0
	global_load_lds_dwordx4 v128, s[30:31]
	s_waitcnt vmcnt(10)
	s_barrier
	s_waitcnt lgkmcnt(0)
	s_waitcnt lgkmcnt(0)
	v_mfma_f32_16x16x32_bf16 v[116:119], v[200:203], v[168:171], v[116:119]
	v_mfma_f32_16x16x32_bf16 v[112:115], v[208:211], v[168:171], v[112:115]
	v_mfma_f32_16x16x32_bf16 v[100:103], v[200:203], v[176:179], v[100:103]
	v_mfma_f32_16x16x32_bf16 v[96:99], v[208:211], v[176:179], v[96:99]
	v_mfma_f32_16x16x32_bf16 v[84:87], v[200:203], v[184:187], v[84:87]
	v_mfma_f32_16x16x32_bf16 v[80:83], v[208:211], v[184:187], v[80:83]
	v_mfma_f32_16x16x32_bf16 v[68:71], v[200:203], v[192:195], v[68:71]
	v_mfma_f32_16x16x32_bf16 v[64:67], v[208:211], v[192:195], v[64:67]
	v_mfma_f32_16x16x32_bf16 v[116:119], v[204:207], v[172:175], v[116:119]
	v_mfma_f32_16x16x32_bf16 v[112:115], v[212:215], v[172:175], v[112:115]
	v_mfma_f32_16x16x32_bf16 v[100:103], v[204:207], v[180:183], v[100:103]
	v_mfma_f32_16x16x32_bf16 v[96:99], v[212:215], v[180:183], v[96:99]
	v_mfma_f32_16x16x32_bf16 v[84:87], v[204:207], v[188:191], v[84:87]
	v_mfma_f32_16x16x32_bf16 v[80:83], v[212:215], v[188:191], v[80:83]
	v_mfma_f32_16x16x32_bf16 v[68:71], v[204:207], v[196:199], v[68:71]
	v_mfma_f32_16x16x32_bf16 v[64:67], v[212:215], v[196:199], v[64:67]
	s_mov_b32 m0, s45
	s_add_u32 s82, s34, 0x80
	s_addc_u32 s83, s35, 0
	s_barrier
	ds_read_b128 v[168:171], v152 offset:16384
	ds_read_b128 v[172:175], v152 offset:17408
	ds_read_b128 v[176:179], v152 offset:18432
	ds_read_b128 v[180:183], v152 offset:19456
	ds_read_b128 v[184:187], v152 offset:20480
	ds_read_b128 v[188:191], v152 offset:21504
	ds_read_b128 v[192:195], v152 offset:22528
	ds_read_b128 v[196:199], v152 offset:23552
	global_load_lds_dwordx4 v134, s[34:35]
	s_mov_b32 m0, s46
	s_nop 0
	global_load_lds_dwordx4 v130, s[34:35]
	s_barrier
	s_waitcnt lgkmcnt(0)
	s_waitcnt lgkmcnt(0)
	v_mfma_f32_16x16x32_bf16 v[60:63], v[144:147], v[168:171], v[60:63]
	v_mfma_f32_16x16x32_bf16 v[56:59], v[160:163], v[168:171], v[56:59]
	v_mfma_f32_16x16x32_bf16 v[44:47], v[144:147], v[176:179], v[44:47]
	v_mfma_f32_16x16x32_bf16 v[40:43], v[160:163], v[176:179], v[40:43]
	v_mfma_f32_16x16x32_bf16 v[28:31], v[144:147], v[184:187], v[28:31]
	v_mfma_f32_16x16x32_bf16 v[24:27], v[160:163], v[184:187], v[24:27]
	v_mfma_f32_16x16x32_bf16 v[12:15], v[144:147], v[192:195], v[12:15]
	v_mfma_f32_16x16x32_bf16 v[8:11], v[160:163], v[192:195], v[8:11]
	v_mfma_f32_16x16x32_bf16 v[60:63], v[156:159], v[172:175], v[60:63]
	v_mfma_f32_16x16x32_bf16 v[56:59], v[164:167], v[172:175], v[56:59]
	v_mfma_f32_16x16x32_bf16 v[44:47], v[156:159], v[180:183], v[44:47]
	v_mfma_f32_16x16x32_bf16 v[40:43], v[164:167], v[180:183], v[40:43]
	v_mfma_f32_16x16x32_bf16 v[28:31], v[156:159], v[188:191], v[28:31]
	v_mfma_f32_16x16x32_bf16 v[24:27], v[164:167], v[188:191], v[24:27]
	v_mfma_f32_16x16x32_bf16 v[12:15], v[156:159], v[196:199], v[12:15]
	v_mfma_f32_16x16x32_bf16 v[8:11], v[164:167], v[196:199], v[8:11]
	s_barrier
	s_add_u32 s62, s30, 0x40000
	s_addc_u32 s63, s31, 0
	s_add_i32 s64, s54, s42
	s_mov_b32 m0, s64
	s_nop 0
	global_load_lds_dwordx4 v132, s[62:63]
	s_add_i32 m0, s64, 0x2000
	s_nop 0
	global_load_lds_dwordx4 v128, s[62:63]
	s_waitcnt vmcnt(8)
	s_barrier
	v_mfma_f32_16x16x32_bf16 v[52:55], v[200:203], v[168:171], v[52:55]
	v_mfma_f32_16x16x32_bf16 v[48:51], v[208:211], v[168:171], v[48:51]
	v_mfma_f32_16x16x32_bf16 v[36:39], v[200:203], v[176:179], v[36:39]
	v_mfma_f32_16x16x32_bf16 v[32:35], v[208:211], v[176:179], v[32:35]
	v_mfma_f32_16x16x32_bf16 v[20:23], v[200:203], v[184:187], v[20:23]
	v_mfma_f32_16x16x32_bf16 v[16:19], v[208:211], v[184:187], v[16:19]
	v_mfma_f32_16x16x32_bf16 v[4:7], v[200:203], v[192:195], v[4:7]
	v_mfma_f32_16x16x32_bf16 v[0:3], v[208:211], v[192:195], v[0:3]
	v_mfma_f32_16x16x32_bf16 v[52:55], v[204:207], v[172:175], v[52:55]
	v_mfma_f32_16x16x32_bf16 v[48:51], v[212:215], v[172:175], v[48:51]
	v_mfma_f32_16x16x32_bf16 v[36:39], v[204:207], v[180:183], v[36:39]
	v_mfma_f32_16x16x32_bf16 v[32:35], v[212:215], v[180:183], v[32:35]
	v_mfma_f32_16x16x32_bf16 v[20:23], v[204:207], v[188:191], v[20:23]
	v_mfma_f32_16x16x32_bf16 v[16:19], v[212:215], v[188:191], v[16:19]
	v_mfma_f32_16x16x32_bf16 v[4:7], v[204:207], v[196:199], v[4:7]
	v_mfma_f32_16x16x32_bf16 v[0:3], v[212:215], v[196:199], v[0:3]
	s_add_i32 s62, 0, 0x18000
	v_add_u32_e32 v155, s62, v149
	s_barrier
.Lg786_mid:
	ds_read_b128 v[144:147], v155
	ds_read_b128 v[156:159], v155 offset:1024
	ds_read_b128 v[160:163], v155 offset:2048
	ds_read_b128 v[164:167], v155 offset:3072
	s_add_u32 s34, s34, 0x40000
	s_addc_u32 s35, s35, 0
	s_mov_b32 m0, s47
	ds_read_b128 v[168:171], v152 offset:32768
	ds_read_b128 v[172:175], v152 offset:33792
	ds_read_b128 v[176:179], v152 offset:34816
	ds_read_b128 v[180:183], v152 offset:35840
	ds_read_b128 v[184:187], v152 offset:36864
	ds_read_b128 v[188:191], v152 offset:37888
	ds_read_b128 v[192:195], v152 offset:38912
	ds_read_b128 v[196:199], v152 offset:39936
	global_load_lds_dwordx4 v134, s[34:35]
	s_mov_b32 m0, s48
	s_nop 0
	global_load_lds_dwordx4 v130, s[34:35]
	s_waitcnt lgkmcnt(8)
	s_barrier
	s_waitcnt lgkmcnt(0)
	s_waitcnt lgkmcnt(0)
	s_add_i32 s34, 0, 0x1c000
	v_add_u32_e32 v155, s34, v149
	v_mfma_f32_16x16x32_bf16 v[124:127], v[144:147], v[168:171], v[124:127]
	ds_read_b128 v[200:203], v155
	v_mfma_f32_16x16x32_bf16 v[120:123], v[160:163], v[168:171], v[120:123]
	v_mfma_f32_16x16x32_bf16 v[108:111], v[144:147], v[176:179], v[108:111]
	ds_read_b128 v[204:207], v155 offset:1024
	v_mfma_f32_16x16x32_bf16 v[104:107], v[160:163], v[176:179], v[104:107]
	v_mfma_f32_16x16x32_bf16 v[92:95], v[144:147], v[184:187], v[92:95]
	ds_read_b128 v[208:211], v155 offset:2048
	v_mfma_f32_16x16x32_bf16 v[88:91], v[160:163], v[184:187], v[88:91]
	v_mfma_f32_16x16x32_bf16 v[76:79], v[144:147], v[192:195], v[76:79]
	ds_read_b128 v[212:215], v155 offset:3072
	v_mfma_f32_16x16x32_bf16 v[72:75], v[160:163], v[192:195], v[72:75]
	v_mfma_f32_16x16x32_bf16 v[124:127], v[156:159], v[172:175], v[124:127]
	v_mfma_f32_16x16x32_bf16 v[120:123], v[164:167], v[172:175], v[120:123]
	v_mfma_f32_16x16x32_bf16 v[108:111], v[156:159], v[180:183], v[108:111]
	v_mfma_f32_16x16x32_bf16 v[104:107], v[164:167], v[180:183], v[104:107]
	v_mfma_f32_16x16x32_bf16 v[92:95], v[156:159], v[188:191], v[92:95]
	v_mfma_f32_16x16x32_bf16 v[88:91], v[164:167], v[188:191], v[88:91]
	v_mfma_f32_16x16x32_bf16 v[76:79], v[156:159], v[196:199], v[76:79]
	v_mfma_f32_16x16x32_bf16 v[72:75], v[164:167], v[196:199], v[72:75]
	s_barrier
	s_add_i32 s35, s62, s42
	s_mov_b32 m0, s35
	global_load_lds_dwordx4 v132, s[80:81]
	s_add_i32 m0, s35, 0x2000
	s_nop 0
	global_load_lds_dwordx4 v128, s[80:81]
	s_waitcnt vmcnt(10)
	s_barrier
	s_waitcnt lgkmcnt(0)
	s_waitcnt lgkmcnt(0)
	v_mfma_f32_16x16x32_bf16 v[116:119], v[200:203], v[168:171], v[116:119]
	v_mfma_f32_16x16x32_bf16 v[112:115], v[208:211], v[168:171], v[112:115]
	v_mfma_f32_16x16x32_bf16 v[100:103], v[200:203], v[176:179], v[100:103]
	v_mfma_f32_16x16x32_bf16 v[96:99], v[208:211], v[176:179], v[96:99]
	v_mfma_f32_16x16x32_bf16 v[84:87], v[200:203], v[184:187], v[84:87]
	v_mfma_f32_16x16x32_bf16 v[80:83], v[208:211], v[184:187], v[80:83]
	v_mfma_f32_16x16x32_bf16 v[68:71], v[200:203], v[192:195], v[68:71]
	v_mfma_f32_16x16x32_bf16 v[64:67], v[208:211], v[192:195], v[64:67]
	v_mfma_f32_16x16x32_bf16 v[116:119], v[204:207], v[172:175], v[116:119]
	v_mfma_f32_16x16x32_bf16 v[112:115], v[212:215], v[172:175], v[112:115]
	v_mfma_f32_16x16x32_bf16 v[100:103], v[204:207], v[180:183], v[100:103]
	v_mfma_f32_16x16x32_bf16 v[96:99], v[212:215], v[180:183], v[96:99]
	v_mfma_f32_16x16x32_bf16 v[84:87], v[204:207], v[188:191], v[84:87]
	v_mfma_f32_16x16x32_bf16 v[80:83], v[212:215], v[188:191], v[80:83]
	v_mfma_f32_16x16x32_bf16 v[68:71], v[204:207], v[196:199], v[68:71]
	v_mfma_f32_16x16x32_bf16 v[64:67], v[212:215], v[196:199], v[64:67]
	s_mov_b32 m0, s50
	s_barrier
	ds_read_b128 v[168:171], v152 offset:49152
	ds_read_b128 v[172:175], v152 offset:50176
	ds_read_b128 v[176:179], v152 offset:51200
	ds_read_b128 v[180:183], v152 offset:52224
	ds_read_b128 v[184:187], v152 offset:53248
	ds_read_b128 v[188:191], v152 offset:54272
	ds_read_b128 v[192:195], v152 offset:55296
	ds_read_b128 v[196:199], v152 offset:56320
	global_load_lds_dwordx4 v134, s[82:83]
	s_mov_b32 m0, s51
	s_nop 0
	global_load_lds_dwordx4 v130, s[82:83]
	s_barrier
	s_waitcnt lgkmcnt(0)
	s_waitcnt lgkmcnt(0)
	v_mfma_f32_16x16x32_bf16 v[60:63], v[144:147], v[168:171], v[60:63]
	v_mfma_f32_16x16x32_bf16 v[56:59], v[160:163], v[168:171], v[56:59]
	v_mfma_f32_16x16x32_bf16 v[44:47], v[144:147], v[176:179], v[44:47]
	v_mfma_f32_16x16x32_bf16 v[40:43], v[160:163], v[176:179], v[40:43]
	v_mfma_f32_16x16x32_bf16 v[28:31], v[144:147], v[184:187], v[28:31]
	v_mfma_f32_16x16x32_bf16 v[24:27], v[160:163], v[184:187], v[24:27]
	v_mfma_f32_16x16x32_bf16 v[12:15], v[144:147], v[192:195], v[12:15]
	v_mfma_f32_16x16x32_bf16 v[8:11], v[160:163], v[192:195], v[8:11]
	v_mfma_f32_16x16x32_bf16 v[60:63], v[156:159], v[172:175], v[60:63]
	v_mfma_f32_16x16x32_bf16 v[56:59], v[164:167], v[172:175], v[56:59]
	v_mfma_f32_16x16x32_bf16 v[44:47], v[156:159], v[180:183], v[44:47]
	v_mfma_f32_16x16x32_bf16 v[40:43], v[164:167], v[180:183], v[40:43]
	v_mfma_f32_16x16x32_bf16 v[28:31], v[156:159], v[188:191], v[28:31]
	v_mfma_f32_16x16x32_bf16 v[24:27], v[164:167], v[188:191], v[24:27]
	v_mfma_f32_16x16x32_bf16 v[12:15], v[156:159], v[196:199], v[12:15]
	v_mfma_f32_16x16x32_bf16 v[8:11], v[164:167], v[196:199], v[8:11]
	s_barrier
	s_add_u32 s30, s30, 0x40080
	s_addc_u32 s31, s31, 0
	s_add_i32 s34, s34, s42
	s_mov_b32 m0, s34
	s_nop 0
	global_load_lds_dwordx4 v132, s[30:31]
	s_add_i32 m0, s34, 0x2000
	s_nop 0
	global_load_lds_dwordx4 v128, s[30:31]
	s_waitcnt vmcnt(8)
	s_barrier
	v_mfma_f32_16x16x32_bf16 v[52:55], v[200:203], v[168:171], v[52:55]
	v_mfma_f32_16x16x32_bf16 v[48:51], v[208:211], v[168:171], v[48:51]
	v_mfma_f32_16x16x32_bf16 v[36:39], v[200:203], v[176:179], v[36:39]
	v_mfma_f32_16x16x32_bf16 v[32:35], v[208:211], v[176:179], v[32:35]
	v_mfma_f32_16x16x32_bf16 v[20:23], v[200:203], v[184:187], v[20:23]
	v_mfma_f32_16x16x32_bf16 v[16:19], v[208:211], v[184:187], v[16:19]
	v_mfma_f32_16x16x32_bf16 v[4:7], v[200:203], v[192:195], v[4:7]
	v_mfma_f32_16x16x32_bf16 v[0:3], v[208:211], v[192:195], v[0:3]
	v_mfma_f32_16x16x32_bf16 v[52:55], v[204:207], v[172:175], v[52:55]
	v_mfma_f32_16x16x32_bf16 v[48:51], v[212:215], v[172:175], v[48:51]
	v_mfma_f32_16x16x32_bf16 v[36:39], v[204:207], v[180:183], v[36:39]
	v_mfma_f32_16x16x32_bf16 v[32:35], v[212:215], v[180:183], v[32:35]
	v_mfma_f32_16x16x32_bf16 v[20:23], v[204:207], v[188:191], v[20:23]
	v_mfma_f32_16x16x32_bf16 v[16:19], v[212:215], v[188:191], v[16:19]
	v_mfma_f32_16x16x32_bf16 v[4:7], v[204:207], v[196:199], v[4:7]
	v_mfma_f32_16x16x32_bf16 v[0:3], v[212:215], v[196:199], v[0:3]
	s_add_i32 s61, s61, 2
	s_add_u32 s28, s28, 0x100
	s_addc_u32 s29, s29, 0
	s_add_u32 s59, s59, 0x100
	s_addc_u32 s60, s60, 0
	s_cmp_gt_u32 s61, 13
	s_barrier
	s_cbranch_scc0 .LBB0_786
	s_setprio 0
	v_lshl_add_u32 v146, s8, 8, v148
	v_ashrrev_i32_e32 v147, 31, v146
	v_lshl_or_b32 v144, s56, 8, v150
	v_lshlrev_b64 v[156:157], 11, v[146:147]
	v_ashrrev_i32_e32 v145, 31, v144
	v_lshl_add_u64 v[156:157], s[10:11], 0, v[156:157]
	v_lshl_add_u64 v[166:167], v[144:145], 1, v[156:157]
	global_load_dwordx4 v[158:161], v[166:167], off
	global_load_dwordx4 v[162:165], v[166:167], off offset:256
	s_mov_b64 s[84:85], 0x8000
	s_mov_b64 s[86:87], 0x28000
	v_lshl_add_u64 v[232:233], v[166:167], 0, s[84:85]
	global_load_dwordx4 v[176:179], v[232:233], off
	global_load_dwordx4 v[180:183], v[232:233], off offset:256
	v_lshl_add_u64 v[232:233], v[232:233], 0, s[84:85]
	global_load_dwordx4 v[184:187], v[232:233], off
	global_load_dwordx4 v[188:191], v[232:233], off offset:256
	v_lshl_add_u64 v[232:233], v[232:233], 0, s[84:85]
	global_load_dwordx4 v[192:195], v[232:233], off
	global_load_dwordx4 v[196:199], v[232:233], off offset:256
	v_lshl_add_u64 v[232:233], v[232:233], 0, s[86:87]
	global_load_dwordx4 v[200:203], v[232:233], off
	global_load_dwordx4 v[204:207], v[232:233], off offset:256
	v_lshl_add_u64 v[232:233], v[232:233], 0, s[84:85]
	global_load_dwordx4 v[208:211], v[232:233], off
	global_load_dwordx4 v[212:215], v[232:233], off offset:256
	v_lshl_add_u64 v[232:233], v[232:233], 0, s[84:85]
	global_load_dwordx4 v[216:219], v[232:233], off
	global_load_dwordx4 v[220:223], v[232:233], off offset:256
	v_lshl_add_u64 v[232:233], v[232:233], 0, s[84:85]
	global_load_dwordx4 v[224:227], v[232:233], off
	global_load_dwordx4 v[228:231], v[232:233], off offset:256
	s_cmpk_gt_u32 s37, 0xff
	s_cbranch_scc1 .Lg786_nox
	s_barrier
	s_setprio 1

.Lg893_noy:
	ds_read_b128 v[152:155], v148
	ds_read_b128 v[156:159], v148 offset:1024
	ds_read_b128 v[160:163], v148 offset:2048
	ds_read_b128 v[164:167], v148 offset:3072
	s_add_u32 s26, s20, 0xfffc0080
	s_addc_u32 s27, s21, -1
	s_cmp_eq_u32 s57, 12
	s_cselect_b32 s29, s13, s27
	s_cselect_b32 s28, s53, s26
	s_cselect_b32 s27, s11, s56
	s_cselect_b32 s26, s54, s55
	s_add_i32 m0, s19, 0xc000
	ds_read_b128 v[168:171], v149
	ds_read_b128 v[172:175], v149 offset:1024
	ds_read_b128 v[176:179], v149 offset:2048
	ds_read_b128 v[180:183], v149 offset:3072
	ds_read_b128 v[184:187], v149 offset:4096
	ds_read_b128 v[188:191], v149 offset:5120
	ds_read_b128 v[192:195], v149 offset:6144
	ds_read_b128 v[196:199], v149 offset:7168
	global_load_lds_dwordx4 v136, s[20:21]
	s_add_i32 m0, s19, 0xe000
	s_nop 0
	global_load_lds_dwordx4 v138, s[20:21]
	s_waitcnt lgkmcnt(8)
	s_barrier
	s_waitcnt lgkmcnt(0)
	s_waitcnt lgkmcnt(0)
	v_mfma_f32_16x16x32_bf16 v[124:127], v[152:155], v[168:171], 0
	ds_read_b128 v[200:203], v150
	v_mfma_f32_16x16x32_bf16 v[120:123], v[160:163], v[168:171], 0
	v_mfma_f32_16x16x32_bf16 v[108:111], v[152:155], v[176:179], 0
	ds_read_b128 v[204:207], v150 offset:1024
	v_mfma_f32_16x16x32_bf16 v[104:107], v[160:163], v[176:179], 0
	v_mfma_f32_16x16x32_bf16 v[92:95], v[152:155], v[184:187], 0
	ds_read_b128 v[208:211], v150 offset:2048
	v_mfma_f32_16x16x32_bf16 v[88:91], v[160:163], v[184:187], 0
	v_mfma_f32_16x16x32_bf16 v[76:79], v[152:155], v[192:195], 0
	ds_read_b128 v[212:215], v150 offset:3072
	v_mfma_f32_16x16x32_bf16 v[72:75], v[160:163], v[192:195], 0
	v_mfma_f32_16x16x32_bf16 v[124:127], v[156:159], v[172:175], v[124:127]
	v_mfma_f32_16x16x32_bf16 v[120:123], v[164:167], v[172:175], v[120:123]
	v_mfma_f32_16x16x32_bf16 v[108:111], v[156:159], v[180:183], v[108:111]
	v_mfma_f32_16x16x32_bf16 v[104:107], v[164:167], v[180:183], v[104:107]
	v_mfma_f32_16x16x32_bf16 v[92:95], v[156:159], v[188:191], v[92:95]
	v_mfma_f32_16x16x32_bf16 v[88:91], v[164:167], v[188:191], v[88:91]
	v_mfma_f32_16x16x32_bf16 v[76:79], v[156:159], v[196:199], v[76:79]
	v_mfma_f32_16x16x32_bf16 v[72:75], v[164:167], v[196:199], v[72:75]
	s_barrier
	s_add_i32 s58, s47, s31
	s_add_u32 s80, s26, 0x80
	s_addc_u32 s81, s27, 0
	s_mov_b32 m0, s58
	global_load_lds_dwordx4 v132, s[26:27]
	s_add_i32 m0, s58, 0x2000
	s_nop 0
	global_load_lds_dwordx4 v128, s[26:27]
	s_waitcnt vmcnt(10)
	s_barrier
	s_waitcnt lgkmcnt(0)
	s_waitcnt lgkmcnt(0)
	v_mfma_f32_16x16x32_bf16 v[116:119], v[200:203], v[168:171], 0
	v_mfma_f32_16x16x32_bf16 v[112:115], v[208:211], v[168:171], 0
	v_mfma_f32_16x16x32_bf16 v[100:103], v[200:203], v[176:179], 0
	v_mfma_f32_16x16x32_bf16 v[96:99], v[208:211], v[176:179], 0
	v_mfma_f32_16x16x32_bf16 v[84:87], v[200:203], v[184:187], 0
	v_mfma_f32_16x16x32_bf16 v[80:83], v[208:211], v[184:187], 0
	v_mfma_f32_16x16x32_bf16 v[68:71], v[200:203], v[192:195], 0
	v_mfma_f32_16x16x32_bf16 v[64:67], v[208:211], v[192:195], 0
	v_mfma_f32_16x16x32_bf16 v[116:119], v[204:207], v[172:175], v[116:119]
	v_mfma_f32_16x16x32_bf16 v[112:115], v[212:215], v[172:175], v[112:115]
	v_mfma_f32_16x16x32_bf16 v[100:103], v[204:207], v[180:183], v[100:103]
	v_mfma_f32_16x16x32_bf16 v[96:99], v[212:215], v[180:183], v[96:99]
	v_mfma_f32_16x16x32_bf16 v[84:87], v[204:207], v[188:191], v[84:87]
	v_mfma_f32_16x16x32_bf16 v[80:83], v[212:215], v[188:191], v[80:83]
	v_mfma_f32_16x16x32_bf16 v[68:71], v[204:207], v[196:199], v[68:71]
	v_mfma_f32_16x16x32_bf16 v[64:67], v[212:215], v[196:199], v[64:67]
	s_mov_b32 m0, s19
	s_add_u32 s82, s28, 0x80
	s_addc_u32 s83, s29, 0
	s_barrier
	ds_read_b128 v[168:171], v149 offset:16384
	ds_read_b128 v[172:175], v149 offset:17408
	ds_read_b128 v[176:179], v149 offset:18432
	ds_read_b128 v[180:183], v149 offset:19456
	ds_read_b128 v[184:187], v149 offset:20480
	ds_read_b128 v[188:191], v149 offset:21504
	ds_read_b128 v[192:195], v149 offset:22528
	ds_read_b128 v[196:199], v149 offset:23552
	global_load_lds_dwordx4 v134, s[28:29]
	s_mov_b32 m0, s42
	s_nop 0
	global_load_lds_dwordx4 v130, s[28:29]
	s_barrier
	s_waitcnt lgkmcnt(0)
	s_waitcnt lgkmcnt(0)
	v_mfma_f32_16x16x32_bf16 v[60:63], v[152:155], v[168:171], 0
	v_mfma_f32_16x16x32_bf16 v[56:59], v[160:163], v[168:171], 0
	v_mfma_f32_16x16x32_bf16 v[44:47], v[152:155], v[176:179], 0
	v_mfma_f32_16x16x32_bf16 v[40:43], v[160:163], v[176:179], 0
	v_mfma_f32_16x16x32_bf16 v[28:31], v[152:155], v[184:187], 0
	v_mfma_f32_16x16x32_bf16 v[24:27], v[160:163], v[184:187], 0
	v_mfma_f32_16x16x32_bf16 v[12:15], v[152:155], v[192:195], 0
	v_mfma_f32_16x16x32_bf16 v[8:11], v[160:163], v[192:195], 0
	v_mfma_f32_16x16x32_bf16 v[60:63], v[156:159], v[172:175], v[60:63]
	v_mfma_f32_16x16x32_bf16 v[56:59], v[164:167], v[172:175], v[56:59]
	v_mfma_f32_16x16x32_bf16 v[44:47], v[156:159], v[180:183], v[44:47]
	v_mfma_f32_16x16x32_bf16 v[40:43], v[164:167], v[180:183], v[40:43]
	v_mfma_f32_16x16x32_bf16 v[28:31], v[156:159], v[188:191], v[28:31]
	v_mfma_f32_16x16x32_bf16 v[24:27], v[164:167], v[188:191], v[24:27]
	v_mfma_f32_16x16x32_bf16 v[12:15], v[156:159], v[196:199], v[12:15]
	v_mfma_f32_16x16x32_bf16 v[8:11], v[164:167], v[196:199], v[8:11]
	s_barrier
	s_add_u32 s58, s26, 0x40000
	s_addc_u32 s59, s27, 0
	s_add_i32 s60, s48, s31
	s_mov_b32 m0, s60
	s_nop 0
	global_load_lds_dwordx4 v132, s[58:59]
	s_add_i32 m0, s60, 0x2000
	s_nop 0
	global_load_lds_dwordx4 v128, s[58:59]
	s_waitcnt vmcnt(8)
	s_barrier
	v_mfma_f32_16x16x32_bf16 v[52:55], v[200:203], v[168:171], 0
	v_mfma_f32_16x16x32_bf16 v[48:51], v[208:211], v[168:171], 0
	v_mfma_f32_16x16x32_bf16 v[36:39], v[200:203], v[176:179], 0
	v_mfma_f32_16x16x32_bf16 v[32:35], v[208:211], v[176:179], 0
	v_mfma_f32_16x16x32_bf16 v[20:23], v[200:203], v[184:187], 0
	v_mfma_f32_16x16x32_bf16 v[16:19], v[208:211], v[184:187], 0
	v_mfma_f32_16x16x32_bf16 v[4:7], v[200:203], v[192:195], 0
	v_mfma_f32_16x16x32_bf16 v[0:3], v[208:211], v[192:195], 0
	v_mfma_f32_16x16x32_bf16 v[52:55], v[204:207], v[172:175], v[52:55]
	v_mfma_f32_16x16x32_bf16 v[48:51], v[212:215], v[172:175], v[48:51]
	v_mfma_f32_16x16x32_bf16 v[36:39], v[204:207], v[180:183], v[36:39]
	v_mfma_f32_16x16x32_bf16 v[32:35], v[212:215], v[180:183], v[32:35]
	v_mfma_f32_16x16x32_bf16 v[20:23], v[204:207], v[188:191], v[20:23]
	v_mfma_f32_16x16x32_bf16 v[16:19], v[212:215], v[188:191], v[16:19]
	v_mfma_f32_16x16x32_bf16 v[4:7], v[204:207], v[196:199], v[4:7]
	v_mfma_f32_16x16x32_bf16 v[0:3], v[212:215], v[196:199], v[0:3]
	s_add_i32 s58, 0, 0x18000
	v_add_u32_e32 v151, s58, v145
	s_barrier
	s_branch .Lg893_mid
.LBB0_893:
	ds_read_b128 v[152:155], v148
	ds_read_b128 v[156:159], v148 offset:1024
	ds_read_b128 v[160:163], v148 offset:2048
	ds_read_b128 v[164:167], v148 offset:3072
	s_add_u32 s26, s20, 0xfffc0080
	s_addc_u32 s27, s21, -1
	s_cmp_eq_u32 s57, 12
	s_cselect_b32 s29, s13, s27
	s_cselect_b32 s28, s53, s26
	s_cselect_b32 s27, s11, s56
	s_cselect_b32 s26, s54, s55
	s_add_i32 m0, s19, 0xc000
	ds_read_b128 v[168:171], v149
	ds_read_b128 v[172:175], v149 offset:1024
	ds_read_b128 v[176:179], v149 offset:2048
	ds_read_b128 v[180:183], v149 offset:3072
	ds_read_b128 v[184:187], v149 offset:4096
	ds_read_b128 v[188:191], v149 offset:5120
	ds_read_b128 v[192:195], v149 offset:6144
	ds_read_b128 v[196:199], v149 offset:7168
	global_load_lds_dwordx4 v136, s[20:21]
	s_add_i32 m0, s19, 0xe000
	s_nop 0
	global_load_lds_dwordx4 v138, s[20:21]
	s_waitcnt lgkmcnt(8)
	s_barrier
	s_waitcnt lgkmcnt(0)
	s_waitcnt lgkmcnt(0)
	v_mfma_f32_16x16x32_bf16 v[124:127], v[152:155], v[168:171], v[124:127]
	ds_read_b128 v[200:203], v150
	v_mfma_f32_16x16x32_bf16 v[120:123], v[160:163], v[168:171], v[120:123]
	v_mfma_f32_16x16x32_bf16 v[108:111], v[152:155], v[176:179], v[108:111]
	ds_read_b128 v[204:207], v150 offset:1024
	v_mfma_f32_16x16x32_bf16 v[104:107], v[160:163], v[176:179], v[104:107]
	v_mfma_f32_16x16x32_bf16 v[92:95], v[152:155], v[184:187], v[92:95]
	ds_read_b128 v[208:211], v150 offset:2048
	v_mfma_f32_16x16x32_bf16 v[88:91], v[160:163], v[184:187], v[88:91]
	v_mfma_f32_16x16x32_bf16 v[76:79], v[152:155], v[192:195], v[76:79]
	ds_read_b128 v[212:215], v150 offset:3072
	v_mfma_f32_16x16x32_bf16 v[72:75], v[160:163], v[192:195], v[72:75]
	v_mfma_f32_16x16x32_bf16 v[124:127], v[156:159], v[172:175], v[124:127]
	v_mfma_f32_16x16x32_bf16 v[120:123], v[164:167], v[172:175], v[120:123]
	v_mfma_f32_16x16x32_bf16 v[108:111], v[156:159], v[180:183], v[108:111]
	v_mfma_f32_16x16x32_bf16 v[104:107], v[164:167], v[180:183], v[104:107]
	v_mfma_f32_16x16x32_bf16 v[92:95], v[156:159], v[188:191], v[92:95]
	v_mfma_f32_16x16x32_bf16 v[88:91], v[164:167], v[188:191], v[88:91]
	v_mfma_f32_16x16x32_bf16 v[76:79], v[156:159], v[196:199], v[76:79]
	v_mfma_f32_16x16x32_bf16 v[72:75], v[164:167], v[196:199], v[72:75]
	s_barrier
	s_add_i32 s58, s47, s31
	s_add_u32 s80, s26, 0x80
	s_addc_u32 s81, s27, 0
	s_mov_b32 m0, s58
	global_load_lds_dwordx4 v132, s[26:27]
	s_add_i32 m0, s58, 0x2000
	s_nop 0
	global_load_lds_dwordx4 v128, s[26:27]
	s_waitcnt vmcnt(10)
	s_barrier
	s_waitcnt lgkmcnt(0)
	s_waitcnt lgkmcnt(0)
	v_mfma_f32_16x16x32_bf16 v[116:119], v[200:203], v[168:171], v[116:119]
	v_mfma_f32_16x16x32_bf16 v[112:115], v[208:211], v[168:171], v[112:115]
	v_mfma_f32_16x16x32_bf16 v[100:103], v[200:203], v[176:179], v[100:103]
	v_mfma_f32_16x16x32_bf16 v[96:99], v[208:211], v[176:179], v[96:99]
	v_mfma_f32_16x16x32_bf16 v[84:87], v[200:203], v[184:187], v[84:87]
	v_mfma_f32_16x16x32_bf16 v[80:83], v[208:211], v[184:187], v[80:83]
	v_mfma_f32_16x16x32_bf16 v[68:71], v[200:203], v[192:195], v[68:71]
	v_mfma_f32_16x16x32_bf16 v[64:67], v[208:211], v[192:195], v[64:67]
	v_mfma_f32_16x16x32_bf16 v[116:119], v[204:207], v[172:175], v[116:119]
	v_mfma_f32_16x16x32_bf16 v[112:115], v[212:215], v[172:175], v[112:115]
	v_mfma_f32_16x16x32_bf16 v[100:103], v[204:207], v[180:183], v[100:103]
	v_mfma_f32_16x16x32_bf16 v[96:99], v[212:215], v[180:183], v[96:99]
	v_mfma_f32_16x16x32_bf16 v[84:87], v[204:207], v[188:191], v[84:87]
	v_mfma_f32_16x16x32_bf16 v[80:83], v[212:215], v[188:191], v[80:83]
	v_mfma_f32_16x16x32_bf16 v[68:71], v[204:207], v[196:199], v[68:71]
	v_mfma_f32_16x16x32_bf16 v[64:67], v[212:215], v[196:199], v[64:67]
	s_mov_b32 m0, s19
	s_add_u32 s82, s28, 0x80
	s_addc_u32 s83, s29, 0
	s_barrier
	ds_read_b128 v[168:171], v149 offset:16384
	ds_read_b128 v[172:175], v149 offset:17408
	ds_read_b128 v[176:179], v149 offset:18432
	ds_read_b128 v[180:183], v149 offset:19456
	ds_read_b128 v[184:187], v149 offset:20480
	ds_read_b128 v[188:191], v149 offset:21504
	ds_read_b128 v[192:195], v149 offset:22528
	ds_read_b128 v[196:199], v149 offset:23552
	global_load_lds_dwordx4 v134, s[28:29]
	s_mov_b32 m0, s42
	s_nop 0
	global_load_lds_dwordx4 v130, s[28:29]
	s_barrier
	s_waitcnt lgkmcnt(0)
	s_waitcnt lgkmcnt(0)
	v_mfma_f32_16x16x32_bf16 v[60:63], v[152:155], v[168:171], v[60:63]
	v_mfma_f32_16x16x32_bf16 v[56:59], v[160:163], v[168:171], v[56:59]
	v_mfma_f32_16x16x32_bf16 v[44:47], v[152:155], v[176:179], v[44:47]
	v_mfma_f32_16x16x32_bf16 v[40:43], v[160:163], v[176:179], v[40:43]
	v_mfma_f32_16x16x32_bf16 v[28:31], v[152:155], v[184:187], v[28:31]
	v_mfma_f32_16x16x32_bf16 v[24:27], v[160:163], v[184:187], v[24:27]
	v_mfma_f32_16x16x32_bf16 v[12:15], v[152:155], v[192:195], v[12:15]
	v_mfma_f32_16x16x32_bf16 v[8:11], v[160:163], v[192:195], v[8:11]
	v_mfma_f32_16x16x32_bf16 v[60:63], v[156:159], v[172:175], v[60:63]
	v_mfma_f32_16x16x32_bf16 v[56:59], v[164:167], v[172:175], v[56:59]
	v_mfma_f32_16x16x32_bf16 v[44:47], v[156:159], v[180:183], v[44:47]
	v_mfma_f32_16x16x32_bf16 v[40:43], v[164:167], v[180:183], v[40:43]
	v_mfma_f32_16x16x32_bf16 v[28:31], v[156:159], v[188:191], v[28:31]
	v_mfma_f32_16x16x32_bf16 v[24:27], v[164:167], v[188:191], v[24:27]
	v_mfma_f32_16x16x32_bf16 v[12:15], v[156:159], v[196:199], v[12:15]
	v_mfma_f32_16x16x32_bf16 v[8:11], v[164:167], v[196:199], v[8:11]
	s_barrier
	s_add_u32 s58, s26, 0x40000
	s_addc_u32 s59, s27, 0
	s_add_i32 s60, s48, s31
	s_mov_b32 m0, s60
	s_nop 0
	global_load_lds_dwordx4 v132, s[58:59]
	s_add_i32 m0, s60, 0x2000
	s_nop 0
	global_load_lds_dwordx4 v128, s[58:59]
	s_waitcnt vmcnt(8)
	s_barrier
	v_mfma_f32_16x16x32_bf16 v[52:55], v[200:203], v[168:171], v[52:55]
	v_mfma_f32_16x16x32_bf16 v[48:51], v[208:211], v[168:171], v[48:51]
	v_mfma_f32_16x16x32_bf16 v[36:39], v[200:203], v[176:179], v[36:39]
	v_mfma_f32_16x16x32_bf16 v[32:35], v[208:211], v[176:179], v[32:35]
	v_mfma_f32_16x16x32_bf16 v[20:23], v[200:203], v[184:187], v[20:23]
	v_mfma_f32_16x16x32_bf16 v[16:19], v[208:211], v[184:187], v[16:19]
	v_mfma_f32_16x16x32_bf16 v[4:7], v[200:203], v[192:195], v[4:7]
	v_mfma_f32_16x16x32_bf16 v[0:3], v[208:211], v[192:195], v[0:3]
	v_mfma_f32_16x16x32_bf16 v[52:55], v[204:207], v[172:175], v[52:55]
	v_mfma_f32_16x16x32_bf16 v[48:51], v[212:215], v[172:175], v[48:51]
	v_mfma_f32_16x16x32_bf16 v[36:39], v[204:207], v[180:183], v[36:39]
	v_mfma_f32_16x16x32_bf16 v[32:35], v[212:215], v[180:183], v[32:35]
	v_mfma_f32_16x16x32_bf16 v[20:23], v[204:207], v[188:191], v[20:23]
	v_mfma_f32_16x16x32_bf16 v[16:19], v[212:215], v[188:191], v[16:19]
	v_mfma_f32_16x16x32_bf16 v[4:7], v[204:207], v[196:199], v[4:7]
	v_mfma_f32_16x16x32_bf16 v[0:3], v[212:215], v[196:199], v[0:3]
	s_add_i32 s58, 0, 0x18000
	v_add_u32_e32 v151, s58, v145
	s_barrier
.Lg893_mid:
	ds_read_b128 v[152:155], v151
	ds_read_b128 v[156:159], v151 offset:1024
	ds_read_b128 v[160:163], v151 offset:2048
	ds_read_b128 v[164:167], v151 offset:3072
	s_add_u32 s28, s28, 0x40000
	s_addc_u32 s29, s29, 0
	s_mov_b32 m0, s43
	ds_read_b128 v[168:171], v149 offset:32768
	ds_read_b128 v[172:175], v149 offset:33792
	ds_read_b128 v[176:179], v149 offset:34816
	ds_read_b128 v[180:183], v149 offset:35840
	ds_read_b128 v[184:187], v149 offset:36864
	ds_read_b128 v[188:191], v149 offset:37888
	ds_read_b128 v[192:195], v149 offset:38912
	ds_read_b128 v[196:199], v149 offset:39936
	global_load_lds_dwordx4 v134, s[28:29]
	s_mov_b32 m0, s44
	s_nop 0
	global_load_lds_dwordx4 v130, s[28:29]
	s_waitcnt lgkmcnt(8)
	s_barrier
	s_waitcnt lgkmcnt(0)
	s_waitcnt lgkmcnt(0)
	s_add_i32 s28, 0, 0x1c000
	v_add_u32_e32 v151, s28, v145
	v_mfma_f32_16x16x32_bf16 v[124:127], v[152:155], v[168:171], v[124:127]
	ds_read_b128 v[200:203], v151
	v_mfma_f32_16x16x32_bf16 v[120:123], v[160:163], v[168:171], v[120:123]
	v_mfma_f32_16x16x32_bf16 v[108:111], v[152:155], v[176:179], v[108:111]
	ds_read_b128 v[204:207], v151 offset:1024
	v_mfma_f32_16x16x32_bf16 v[104:107], v[160:163], v[176:179], v[104:107]
	v_mfma_f32_16x16x32_bf16 v[92:95], v[152:155], v[184:187], v[92:95]
	ds_read_b128 v[208:211], v151 offset:2048
	v_mfma_f32_16x16x32_bf16 v[88:91], v[160:163], v[184:187], v[88:91]
	v_mfma_f32_16x16x32_bf16 v[76:79], v[152:155], v[192:195], v[76:79]
	ds_read_b128 v[212:215], v151 offset:3072
	v_mfma_f32_16x16x32_bf16 v[72:75], v[160:163], v[192:195], v[72:75]
	v_mfma_f32_16x16x32_bf16 v[124:127], v[156:159], v[172:175], v[124:127]
	v_mfma_f32_16x16x32_bf16 v[120:123], v[164:167], v[172:175], v[120:123]
	v_mfma_f32_16x16x32_bf16 v[108:111], v[156:159], v[180:183], v[108:111]
	v_mfma_f32_16x16x32_bf16 v[104:107], v[164:167], v[180:183], v[104:107]
	v_mfma_f32_16x16x32_bf16 v[92:95], v[156:159], v[188:191], v[92:95]
	v_mfma_f32_16x16x32_bf16 v[88:91], v[164:167], v[188:191], v[88:91]
	v_mfma_f32_16x16x32_bf16 v[76:79], v[156:159], v[196:199], v[76:79]
	v_mfma_f32_16x16x32_bf16 v[72:75], v[164:167], v[196:199], v[72:75]
	s_barrier
	s_add_i32 s29, s58, s31
	s_mov_b32 m0, s29
	global_load_lds_dwordx4 v132, s[80:81]
	s_add_i32 m0, s29, 0x2000
	s_nop 0
	global_load_lds_dwordx4 v128, s[80:81]
	s_waitcnt vmcnt(10)
	s_barrier
	s_waitcnt lgkmcnt(0)
	s_waitcnt lgkmcnt(0)
	v_mfma_f32_16x16x32_bf16 v[116:119], v[200:203], v[168:171], v[116:119]
	v_mfma_f32_16x16x32_bf16 v[112:115], v[208:211], v[168:171], v[112:115]
	v_mfma_f32_16x16x32_bf16 v[100:103], v[200:203], v[176:179], v[100:103]
	v_mfma_f32_16x16x32_bf16 v[96:99], v[208:211], v[176:179], v[96:99]
	v_mfma_f32_16x16x32_bf16 v[84:87], v[200:203], v[184:187], v[84:87]
	v_mfma_f32_16x16x32_bf16 v[80:83], v[208:211], v[184:187], v[80:83]
	v_mfma_f32_16x16x32_bf16 v[68:71], v[200:203], v[192:195], v[68:71]
	v_mfma_f32_16x16x32_bf16 v[64:67], v[208:211], v[192:195], v[64:67]
	v_mfma_f32_16x16x32_bf16 v[116:119], v[204:207], v[172:175], v[116:119]
	v_mfma_f32_16x16x32_bf16 v[112:115], v[212:215], v[172:175], v[112:115]
	v_mfma_f32_16x16x32_bf16 v[100:103], v[204:207], v[180:183], v[100:103]
	v_mfma_f32_16x16x32_bf16 v[96:99], v[212:215], v[180:183], v[96:99]
	v_mfma_f32_16x16x32_bf16 v[84:87], v[204:207], v[188:191], v[84:87]
	v_mfma_f32_16x16x32_bf16 v[80:83], v[212:215], v[188:191], v[80:83]
	v_mfma_f32_16x16x32_bf16 v[68:71], v[204:207], v[196:199], v[68:71]
	v_mfma_f32_16x16x32_bf16 v[64:67], v[212:215], v[196:199], v[64:67]
	s_mov_b32 m0, s45
	s_barrier
	ds_read_b128 v[168:171], v149 offset:49152
	ds_read_b128 v[172:175], v149 offset:50176
	ds_read_b128 v[176:179], v149 offset:51200
	ds_read_b128 v[180:183], v149 offset:52224
	ds_read_b128 v[184:187], v149 offset:53248
	ds_read_b128 v[188:191], v149 offset:54272
	ds_read_b128 v[192:195], v149 offset:55296
	ds_read_b128 v[196:199], v149 offset:56320
	global_load_lds_dwordx4 v134, s[82:83]
	s_mov_b32 m0, s46
	s_nop 0
	global_load_lds_dwordx4 v130, s[82:83]
	s_barrier
	s_waitcnt lgkmcnt(0)
	s_waitcnt lgkmcnt(0)
	v_mfma_f32_16x16x32_bf16 v[60:63], v[152:155], v[168:171], v[60:63]
	v_mfma_f32_16x16x32_bf16 v[56:59], v[160:163], v[168:171], v[56:59]
	v_mfma_f32_16x16x32_bf16 v[44:47], v[152:155], v[176:179], v[44:47]
	v_mfma_f32_16x16x32_bf16 v[40:43], v[160:163], v[176:179], v[40:43]
	v_mfma_f32_16x16x32_bf16 v[28:31], v[152:155], v[184:187], v[28:31]
	v_mfma_f32_16x16x32_bf16 v[24:27], v[160:163], v[184:187], v[24:27]
	v_mfma_f32_16x16x32_bf16 v[12:15], v[152:155], v[192:195], v[12:15]
	v_mfma_f32_16x16x32_bf16 v[8:11], v[160:163], v[192:195], v[8:11]
	v_mfma_f32_16x16x32_bf16 v[60:63], v[156:159], v[172:175], v[60:63]
	v_mfma_f32_16x16x32_bf16 v[56:59], v[164:167], v[172:175], v[56:59]
	v_mfma_f32_16x16x32_bf16 v[44:47], v[156:159], v[180:183], v[44:47]
	v_mfma_f32_16x16x32_bf16 v[40:43], v[164:167], v[180:183], v[40:43]
	v_mfma_f32_16x16x32_bf16 v[28:31], v[156:159], v[188:191], v[28:31]
	v_mfma_f32_16x16x32_bf16 v[24:27], v[164:167], v[188:191], v[24:27]
	v_mfma_f32_16x16x32_bf16 v[12:15], v[156:159], v[196:199], v[12:15]
	v_mfma_f32_16x16x32_bf16 v[8:11], v[164:167], v[196:199], v[8:11]
	s_barrier
	s_add_u32 s26, s26, 0x40080
	s_addc_u32 s27, s27, 0
	s_add_i32 s28, s28, s31
	s_mov_b32 m0, s28
	s_nop 0
	global_load_lds_dwordx4 v132, s[26:27]
	s_add_i32 m0, s28, 0x2000
	s_nop 0
	global_load_lds_dwordx4 v128, s[26:27]
	s_waitcnt vmcnt(8)
	s_barrier
	v_mfma_f32_16x16x32_bf16 v[52:55], v[200:203], v[168:171], v[52:55]
	v_mfma_f32_16x16x32_bf16 v[48:51], v[208:211], v[168:171], v[48:51]
	v_mfma_f32_16x16x32_bf16 v[36:39], v[200:203], v[176:179], v[36:39]
	v_mfma_f32_16x16x32_bf16 v[32:35], v[208:211], v[176:179], v[32:35]
	v_mfma_f32_16x16x32_bf16 v[20:23], v[200:203], v[184:187], v[20:23]
	v_mfma_f32_16x16x32_bf16 v[16:19], v[208:211], v[184:187], v[16:19]
	v_mfma_f32_16x16x32_bf16 v[4:7], v[200:203], v[192:195], v[4:7]
	v_mfma_f32_16x16x32_bf16 v[0:3], v[208:211], v[192:195], v[0:3]
	v_mfma_f32_16x16x32_bf16 v[52:55], v[204:207], v[172:175], v[52:55]
	v_mfma_f32_16x16x32_bf16 v[48:51], v[212:215], v[172:175], v[48:51]
	v_mfma_f32_16x16x32_bf16 v[36:39], v[204:207], v[180:183], v[36:39]
	v_mfma_f32_16x16x32_bf16 v[32:35], v[212:215], v[180:183], v[32:35]
	v_mfma_f32_16x16x32_bf16 v[20:23], v[204:207], v[188:191], v[20:23]
	v_mfma_f32_16x16x32_bf16 v[16:19], v[212:215], v[188:191], v[16:19]
	v_mfma_f32_16x16x32_bf16 v[4:7], v[204:207], v[196:199], v[4:7]
	v_mfma_f32_16x16x32_bf16 v[0:3], v[212:215], v[196:199], v[0:3]
	s_add_i32 s57, s57, 2
	s_add_u32 s20, s20, 0x100
	s_addc_u32 s21, s21, 0
	s_add_u32 s55, s55, 0x100
	s_addc_u32 s56, s56, 0
	s_cmp_gt_u32 s57, 13
	s_barrier
	s_cbranch_scc0 .LBB0_893
	s_setprio 0
	s_cmpk_gt_u32 s30, 0xff
	s_cbranch_scc1 .Lg893_nox
	s_barrier
	s_setprio 1

.Lg973_noy:
	ds_read_b128 v[146:149], v203
	ds_read_b128 v[150:153], v203 offset:1024
	ds_read_b128 v[154:157], v203 offset:2048
	ds_read_b128 v[158:161], v203 offset:3072
	s_add_u32 s22, s20, 0x100
	s_addc_u32 s23, s21, 0
	s_cmp_eq_u32 s56, 40
	s_cselect_b32 s27, s5, s23
	s_cselect_b32 s26, s4, s22
	s_cselect_b32 s25, s7, s55
	s_cselect_b32 s24, s6, s54
	s_add_i32 m0, s37, 0xc000
	ds_read_b128 v[162:165], v204
	ds_read_b128 v[166:169], v204 offset:1024
	ds_read_b128 v[170:173], v204 offset:2048
	ds_read_b128 v[174:177], v204 offset:3072
	ds_read_b128 v[178:181], v204 offset:4096
	ds_read_b128 v[182:185], v204 offset:5120
	ds_read_b128 v[186:189], v204 offset:6144
	ds_read_b128 v[190:193], v204 offset:7168
	global_load_lds_dwordx4 v138, s[20:21]
	s_add_i32 m0, s37, 0xe000
	s_nop 0
	global_load_lds_dwordx4 v140, s[20:21]
	s_waitcnt lgkmcnt(8)
	s_barrier
	s_waitcnt lgkmcnt(0)
	s_waitcnt lgkmcnt(0)
	v_mfma_f32_16x16x32_bf16 v[124:127], v[146:149], v[162:165], 0
	ds_read_b128 v[194:197], v205
	v_mfma_f32_16x16x32_bf16 v[120:123], v[154:157], v[162:165], 0
	v_mfma_f32_16x16x32_bf16 v[108:111], v[146:149], v[170:173], 0
	ds_read_b128 v[208:211], v205 offset:1024
	v_mfma_f32_16x16x32_bf16 v[104:107], v[154:157], v[170:173], 0
	v_mfma_f32_16x16x32_bf16 v[92:95], v[146:149], v[178:181], 0
	ds_read_b128 v[212:215], v205 offset:2048
	v_mfma_f32_16x16x32_bf16 v[88:91], v[154:157], v[178:181], 0
	v_mfma_f32_16x16x32_bf16 v[76:79], v[146:149], v[186:189], 0
	ds_read_b128 v[216:219], v205 offset:3072
	v_mfma_f32_16x16x32_bf16 v[72:75], v[154:157], v[186:189], 0
	v_mfma_f32_16x16x32_bf16 v[124:127], v[150:153], v[166:169], v[124:127]
	v_mfma_f32_16x16x32_bf16 v[120:123], v[158:161], v[166:169], v[120:123]
	v_mfma_f32_16x16x32_bf16 v[108:111], v[150:153], v[174:177], v[108:111]
	v_mfma_f32_16x16x32_bf16 v[104:107], v[158:161], v[174:177], v[104:107]
	v_mfma_f32_16x16x32_bf16 v[92:95], v[150:153], v[182:185], v[92:95]
	v_mfma_f32_16x16x32_bf16 v[88:91], v[158:161], v[182:185], v[88:91]
	v_mfma_f32_16x16x32_bf16 v[76:79], v[150:153], v[190:193], v[76:79]
	v_mfma_f32_16x16x32_bf16 v[72:75], v[158:161], v[190:193], v[72:75]
	s_barrier
	s_add_i32 s20, s47, s36
	s_add_u32 s80, s24, 0x80
	s_addc_u32 s81, s25, 0
	s_mov_b32 m0, s20
	global_load_lds_dwordx4 v130, s[24:25]
	s_add_i32 m0, s20, 0x2000
	s_nop 0
	global_load_lds_dwordx4 v134, s[24:25]
	s_waitcnt vmcnt(10)
	s_barrier
	s_waitcnt lgkmcnt(0)
	s_waitcnt lgkmcnt(0)
	v_mfma_f32_16x16x32_bf16 v[116:119], v[194:197], v[162:165], 0
	v_mfma_f32_16x16x32_bf16 v[112:115], v[212:215], v[162:165], 0
	v_mfma_f32_16x16x32_bf16 v[100:103], v[194:197], v[170:173], 0
	v_mfma_f32_16x16x32_bf16 v[96:99], v[212:215], v[170:173], 0
	v_mfma_f32_16x16x32_bf16 v[84:87], v[194:197], v[178:181], 0
	v_mfma_f32_16x16x32_bf16 v[80:83], v[212:215], v[178:181], 0
	v_mfma_f32_16x16x32_bf16 v[68:71], v[194:197], v[186:189], 0
	v_mfma_f32_16x16x32_bf16 v[64:67], v[212:215], v[186:189], 0
	v_mfma_f32_16x16x32_bf16 v[116:119], v[208:211], v[166:169], v[116:119]
	v_mfma_f32_16x16x32_bf16 v[112:115], v[216:219], v[166:169], v[112:115]
	v_mfma_f32_16x16x32_bf16 v[100:103], v[208:211], v[174:177], v[100:103]
	v_mfma_f32_16x16x32_bf16 v[96:99], v[216:219], v[174:177], v[96:99]
	v_mfma_f32_16x16x32_bf16 v[84:87], v[208:211], v[182:185], v[84:87]
	v_mfma_f32_16x16x32_bf16 v[80:83], v[216:219], v[182:185], v[80:83]
	v_mfma_f32_16x16x32_bf16 v[68:71], v[208:211], v[190:193], v[68:71]
	v_mfma_f32_16x16x32_bf16 v[64:67], v[216:219], v[190:193], v[64:67]
	s_mov_b32 m0, s37
	s_add_u32 s82, s26, 0x80
	s_addc_u32 s83, s27, 0
	s_barrier
	ds_read_b128 v[162:165], v204 offset:16384
	ds_read_b128 v[166:169], v204 offset:17408
	ds_read_b128 v[170:173], v204 offset:18432
	ds_read_b128 v[174:177], v204 offset:19456
	ds_read_b128 v[178:181], v204 offset:20480
	ds_read_b128 v[182:185], v204 offset:21504
	ds_read_b128 v[186:189], v204 offset:22528
	ds_read_b128 v[190:193], v204 offset:23552
	global_load_lds_dwordx4 v128, s[26:27]
	s_mov_b32 m0, s38
	s_nop 0
	global_load_lds_dwordx4 v132, s[26:27]
	s_barrier
	s_waitcnt lgkmcnt(0)
	s_waitcnt lgkmcnt(0)
	v_mfma_f32_16x16x32_bf16 v[60:63], v[146:149], v[162:165], 0
	v_mfma_f32_16x16x32_bf16 v[56:59], v[154:157], v[162:165], 0
	v_mfma_f32_16x16x32_bf16 v[44:47], v[146:149], v[170:173], 0
	v_mfma_f32_16x16x32_bf16 v[40:43], v[154:157], v[170:173], 0
	v_mfma_f32_16x16x32_bf16 v[28:31], v[146:149], v[178:181], 0
	v_mfma_f32_16x16x32_bf16 v[24:27], v[154:157], v[178:181], 0
	v_mfma_f32_16x16x32_bf16 v[12:15], v[146:149], v[186:189], 0
	v_mfma_f32_16x16x32_bf16 v[8:11], v[154:157], v[186:189], 0
	v_mfma_f32_16x16x32_bf16 v[60:63], v[150:153], v[166:169], v[60:63]
	v_mfma_f32_16x16x32_bf16 v[56:59], v[158:161], v[166:169], v[56:59]
	v_mfma_f32_16x16x32_bf16 v[44:47], v[150:153], v[174:177], v[44:47]
	v_mfma_f32_16x16x32_bf16 v[40:43], v[158:161], v[174:177], v[40:43]
	v_mfma_f32_16x16x32_bf16 v[28:31], v[150:153], v[182:185], v[28:31]
	v_mfma_f32_16x16x32_bf16 v[24:27], v[158:161], v[182:185], v[24:27]
	v_mfma_f32_16x16x32_bf16 v[12:15], v[150:153], v[190:193], v[12:15]
	v_mfma_f32_16x16x32_bf16 v[8:11], v[158:161], v[190:193], v[8:11]
	s_barrier
	s_add_u32 s20, s24, 0xb0000
	s_addc_u32 s21, s25, 0
	s_add_i32 s57, s48, s36
	s_mov_b32 m0, s57
	s_nop 0
	global_load_lds_dwordx4 v130, s[20:21]
	s_add_i32 m0, s57, 0x2000
	s_nop 0
	global_load_lds_dwordx4 v134, s[20:21]
	s_waitcnt vmcnt(8)
	s_barrier
	v_mfma_f32_16x16x32_bf16 v[52:55], v[194:197], v[162:165], 0
	v_mfma_f32_16x16x32_bf16 v[48:51], v[212:215], v[162:165], 0
	v_mfma_f32_16x16x32_bf16 v[36:39], v[194:197], v[170:173], 0
	v_mfma_f32_16x16x32_bf16 v[32:35], v[212:215], v[170:173], 0
	v_mfma_f32_16x16x32_bf16 v[20:23], v[194:197], v[178:181], 0
	v_mfma_f32_16x16x32_bf16 v[16:19], v[212:215], v[178:181], 0
	v_mfma_f32_16x16x32_bf16 v[4:7], v[194:197], v[186:189], 0
	v_mfma_f32_16x16x32_bf16 v[0:3], v[212:215], v[186:189], 0
	v_mfma_f32_16x16x32_bf16 v[52:55], v[208:211], v[166:169], v[52:55]
	v_mfma_f32_16x16x32_bf16 v[48:51], v[216:219], v[166:169], v[48:51]
	v_mfma_f32_16x16x32_bf16 v[36:39], v[208:211], v[174:177], v[36:39]
	v_mfma_f32_16x16x32_bf16 v[32:35], v[216:219], v[174:177], v[32:35]
	v_mfma_f32_16x16x32_bf16 v[20:23], v[208:211], v[182:185], v[20:23]
	v_mfma_f32_16x16x32_bf16 v[16:19], v[216:219], v[182:185], v[16:19]
	v_mfma_f32_16x16x32_bf16 v[4:7], v[208:211], v[190:193], v[4:7]
	v_mfma_f32_16x16x32_bf16 v[0:3], v[216:219], v[190:193], v[0:3]
	s_add_i32 s57, 0, 0x18000
	v_add_u32_e32 v158, s57, v201
	s_barrier
	s_branch .Lg973_mid
.LBB0_973:
	ds_read_b128 v[146:149], v203
	ds_read_b128 v[150:153], v203 offset:1024
	ds_read_b128 v[154:157], v203 offset:2048
	ds_read_b128 v[158:161], v203 offset:3072
	s_add_u32 s22, s20, 0x100
	s_addc_u32 s23, s21, 0
	s_cmp_eq_u32 s56, 40
	s_cselect_b32 s27, s5, s23
	s_cselect_b32 s26, s4, s22
	s_cselect_b32 s25, s7, s55
	s_cselect_b32 s24, s6, s54
	s_add_i32 m0, s37, 0xc000
	ds_read_b128 v[162:165], v204
	ds_read_b128 v[166:169], v204 offset:1024
	ds_read_b128 v[170:173], v204 offset:2048
	ds_read_b128 v[174:177], v204 offset:3072
	ds_read_b128 v[178:181], v204 offset:4096
	ds_read_b128 v[182:185], v204 offset:5120
	ds_read_b128 v[186:189], v204 offset:6144
	ds_read_b128 v[190:193], v204 offset:7168
	global_load_lds_dwordx4 v138, s[20:21]
	s_add_i32 m0, s37, 0xe000
	s_nop 0
	global_load_lds_dwordx4 v140, s[20:21]
	s_waitcnt lgkmcnt(8)
	s_barrier
	s_waitcnt lgkmcnt(0)
	s_waitcnt lgkmcnt(0)
	v_mfma_f32_16x16x32_bf16 v[124:127], v[146:149], v[162:165], v[124:127]
	ds_read_b128 v[194:197], v205
	v_mfma_f32_16x16x32_bf16 v[120:123], v[154:157], v[162:165], v[120:123]
	v_mfma_f32_16x16x32_bf16 v[108:111], v[146:149], v[170:173], v[108:111]
	ds_read_b128 v[208:211], v205 offset:1024
	v_mfma_f32_16x16x32_bf16 v[104:107], v[154:157], v[170:173], v[104:107]
	v_mfma_f32_16x16x32_bf16 v[92:95], v[146:149], v[178:181], v[92:95]
	ds_read_b128 v[212:215], v205 offset:2048
	v_mfma_f32_16x16x32_bf16 v[88:91], v[154:157], v[178:181], v[88:91]
	v_mfma_f32_16x16x32_bf16 v[76:79], v[146:149], v[186:189], v[76:79]
	ds_read_b128 v[216:219], v205 offset:3072
	v_mfma_f32_16x16x32_bf16 v[72:75], v[154:157], v[186:189], v[72:75]
	v_mfma_f32_16x16x32_bf16 v[124:127], v[150:153], v[166:169], v[124:127]
	v_mfma_f32_16x16x32_bf16 v[120:123], v[158:161], v[166:169], v[120:123]
	v_mfma_f32_16x16x32_bf16 v[108:111], v[150:153], v[174:177], v[108:111]
	v_mfma_f32_16x16x32_bf16 v[104:107], v[158:161], v[174:177], v[104:107]
	v_mfma_f32_16x16x32_bf16 v[92:95], v[150:153], v[182:185], v[92:95]
	v_mfma_f32_16x16x32_bf16 v[88:91], v[158:161], v[182:185], v[88:91]
	v_mfma_f32_16x16x32_bf16 v[76:79], v[150:153], v[190:193], v[76:79]
	v_mfma_f32_16x16x32_bf16 v[72:75], v[158:161], v[190:193], v[72:75]
	s_barrier
	s_add_i32 s20, s47, s36
	s_add_u32 s80, s24, 0x80
	s_addc_u32 s81, s25, 0
	s_mov_b32 m0, s20
	global_load_lds_dwordx4 v130, s[24:25]
	s_add_i32 m0, s20, 0x2000
	s_nop 0
	global_load_lds_dwordx4 v134, s[24:25]
	s_waitcnt vmcnt(10)
	s_barrier
	s_waitcnt lgkmcnt(0)
	s_waitcnt lgkmcnt(0)
	v_mfma_f32_16x16x32_bf16 v[116:119], v[194:197], v[162:165], v[116:119]
	v_mfma_f32_16x16x32_bf16 v[112:115], v[212:215], v[162:165], v[112:115]
	v_mfma_f32_16x16x32_bf16 v[100:103], v[194:197], v[170:173], v[100:103]
	v_mfma_f32_16x16x32_bf16 v[96:99], v[212:215], v[170:173], v[96:99]
	v_mfma_f32_16x16x32_bf16 v[84:87], v[194:197], v[178:181], v[84:87]
	v_mfma_f32_16x16x32_bf16 v[80:83], v[212:215], v[178:181], v[80:83]
	v_mfma_f32_16x16x32_bf16 v[68:71], v[194:197], v[186:189], v[68:71]
	v_mfma_f32_16x16x32_bf16 v[64:67], v[212:215], v[186:189], v[64:67]
	v_mfma_f32_16x16x32_bf16 v[116:119], v[208:211], v[166:169], v[116:119]
	v_mfma_f32_16x16x32_bf16 v[112:115], v[216:219], v[166:169], v[112:115]
	v_mfma_f32_16x16x32_bf16 v[100:103], v[208:211], v[174:177], v[100:103]
	v_mfma_f32_16x16x32_bf16 v[96:99], v[216:219], v[174:177], v[96:99]
	v_mfma_f32_16x16x32_bf16 v[84:87], v[208:211], v[182:185], v[84:87]
	v_mfma_f32_16x16x32_bf16 v[80:83], v[216:219], v[182:185], v[80:83]
	v_mfma_f32_16x16x32_bf16 v[68:71], v[208:211], v[190:193], v[68:71]
	v_mfma_f32_16x16x32_bf16 v[64:67], v[216:219], v[190:193], v[64:67]
	s_mov_b32 m0, s37
	s_add_u32 s82, s26, 0x80
	s_addc_u32 s83, s27, 0
	s_barrier
	ds_read_b128 v[162:165], v204 offset:16384
	ds_read_b128 v[166:169], v204 offset:17408
	ds_read_b128 v[170:173], v204 offset:18432
	ds_read_b128 v[174:177], v204 offset:19456
	ds_read_b128 v[178:181], v204 offset:20480
	ds_read_b128 v[182:185], v204 offset:21504
	ds_read_b128 v[186:189], v204 offset:22528
	ds_read_b128 v[190:193], v204 offset:23552
	global_load_lds_dwordx4 v128, s[26:27]
	s_mov_b32 m0, s38
	s_nop 0
	global_load_lds_dwordx4 v132, s[26:27]
	s_barrier
	s_waitcnt lgkmcnt(0)
	s_waitcnt lgkmcnt(0)
	v_mfma_f32_16x16x32_bf16 v[60:63], v[146:149], v[162:165], v[60:63]
	v_mfma_f32_16x16x32_bf16 v[56:59], v[154:157], v[162:165], v[56:59]
	v_mfma_f32_16x16x32_bf16 v[44:47], v[146:149], v[170:173], v[44:47]
	v_mfma_f32_16x16x32_bf16 v[40:43], v[154:157], v[170:173], v[40:43]
	v_mfma_f32_16x16x32_bf16 v[28:31], v[146:149], v[178:181], v[28:31]
	v_mfma_f32_16x16x32_bf16 v[24:27], v[154:157], v[178:181], v[24:27]
	v_mfma_f32_16x16x32_bf16 v[12:15], v[146:149], v[186:189], v[12:15]
	v_mfma_f32_16x16x32_bf16 v[8:11], v[154:157], v[186:189], v[8:11]
	v_mfma_f32_16x16x32_bf16 v[60:63], v[150:153], v[166:169], v[60:63]
	v_mfma_f32_16x16x32_bf16 v[56:59], v[158:161], v[166:169], v[56:59]
	v_mfma_f32_16x16x32_bf16 v[44:47], v[150:153], v[174:177], v[44:47]
	v_mfma_f32_16x16x32_bf16 v[40:43], v[158:161], v[174:177], v[40:43]
	v_mfma_f32_16x16x32_bf16 v[28:31], v[150:153], v[182:185], v[28:31]
	v_mfma_f32_16x16x32_bf16 v[24:27], v[158:161], v[182:185], v[24:27]
	v_mfma_f32_16x16x32_bf16 v[12:15], v[150:153], v[190:193], v[12:15]
	v_mfma_f32_16x16x32_bf16 v[8:11], v[158:161], v[190:193], v[8:11]
	s_barrier
	s_add_u32 s20, s24, 0xb0000
	s_addc_u32 s21, s25, 0
	s_add_i32 s57, s48, s36
	s_mov_b32 m0, s57
	s_nop 0
	global_load_lds_dwordx4 v130, s[20:21]
	s_add_i32 m0, s57, 0x2000
	s_nop 0
	global_load_lds_dwordx4 v134, s[20:21]
	s_waitcnt vmcnt(8)
	s_barrier
	v_mfma_f32_16x16x32_bf16 v[52:55], v[194:197], v[162:165], v[52:55]
	v_mfma_f32_16x16x32_bf16 v[48:51], v[212:215], v[162:165], v[48:51]
	v_mfma_f32_16x16x32_bf16 v[36:39], v[194:197], v[170:173], v[36:39]
	v_mfma_f32_16x16x32_bf16 v[32:35], v[212:215], v[170:173], v[32:35]
	v_mfma_f32_16x16x32_bf16 v[20:23], v[194:197], v[178:181], v[20:23]
	v_mfma_f32_16x16x32_bf16 v[16:19], v[212:215], v[178:181], v[16:19]
	v_mfma_f32_16x16x32_bf16 v[4:7], v[194:197], v[186:189], v[4:7]
	v_mfma_f32_16x16x32_bf16 v[0:3], v[212:215], v[186:189], v[0:3]
	v_mfma_f32_16x16x32_bf16 v[52:55], v[208:211], v[166:169], v[52:55]
	v_mfma_f32_16x16x32_bf16 v[48:51], v[216:219], v[166:169], v[48:51]
	v_mfma_f32_16x16x32_bf16 v[36:39], v[208:211], v[174:177], v[36:39]
	v_mfma_f32_16x16x32_bf16 v[32:35], v[216:219], v[174:177], v[32:35]
	v_mfma_f32_16x16x32_bf16 v[20:23], v[208:211], v[182:185], v[20:23]
	v_mfma_f32_16x16x32_bf16 v[16:19], v[216:219], v[182:185], v[16:19]
	v_mfma_f32_16x16x32_bf16 v[4:7], v[208:211], v[190:193], v[4:7]
	v_mfma_f32_16x16x32_bf16 v[0:3], v[216:219], v[190:193], v[0:3]
	s_add_i32 s57, 0, 0x18000
	v_add_u32_e32 v158, s57, v201
	s_barrier
.Lg973_mid:
	ds_read_b128 v[146:149], v158
	ds_read_b128 v[150:153], v158 offset:1024
	ds_read_b128 v[154:157], v158 offset:2048
	ds_read_b128 v[158:161], v158 offset:3072
	s_add_u32 s20, s26, 0xb0000
	s_addc_u32 s21, s27, 0
	s_mov_b32 m0, s39
	ds_read_b128 v[162:165], v204 offset:32768
	ds_read_b128 v[166:169], v204 offset:33792
	ds_read_b128 v[170:173], v204 offset:34816
	ds_read_b128 v[174:177], v204 offset:35840
	ds_read_b128 v[178:181], v204 offset:36864
	ds_read_b128 v[182:185], v204 offset:37888
	ds_read_b128 v[186:189], v204 offset:38912
	ds_read_b128 v[190:193], v204 offset:39936
	global_load_lds_dwordx4 v128, s[20:21]
	s_mov_b32 m0, s40
	s_nop 0
	global_load_lds_dwordx4 v132, s[20:21]
	s_waitcnt lgkmcnt(8)
	s_barrier
	s_waitcnt lgkmcnt(0)
	s_waitcnt lgkmcnt(0)
	s_add_i32 s26, 0, 0x1c000
	v_add_u32_e32 v216, s26, v201
	v_mfma_f32_16x16x32_bf16 v[124:127], v[146:149], v[162:165], v[124:127]
	ds_read_b128 v[194:197], v216
	v_mfma_f32_16x16x32_bf16 v[120:123], v[154:157], v[162:165], v[120:123]
	v_mfma_f32_16x16x32_bf16 v[108:111], v[146:149], v[170:173], v[108:111]
	ds_read_b128 v[208:211], v216 offset:1024
	v_mfma_f32_16x16x32_bf16 v[104:107], v[154:157], v[170:173], v[104:107]
	v_mfma_f32_16x16x32_bf16 v[92:95], v[146:149], v[178:181], v[92:95]
	ds_read_b128 v[212:215], v216 offset:2048
	v_mfma_f32_16x16x32_bf16 v[88:91], v[154:157], v[178:181], v[88:91]
	v_mfma_f32_16x16x32_bf16 v[76:79], v[146:149], v[186:189], v[76:79]
	ds_read_b128 v[216:219], v216 offset:3072
	v_mfma_f32_16x16x32_bf16 v[72:75], v[154:157], v[186:189], v[72:75]
	v_mfma_f32_16x16x32_bf16 v[124:127], v[150:153], v[166:169], v[124:127]
	v_mfma_f32_16x16x32_bf16 v[120:123], v[158:161], v[166:169], v[120:123]
	v_mfma_f32_16x16x32_bf16 v[108:111], v[150:153], v[174:177], v[108:111]
	v_mfma_f32_16x16x32_bf16 v[104:107], v[158:161], v[174:177], v[104:107]
	v_mfma_f32_16x16x32_bf16 v[92:95], v[150:153], v[182:185], v[92:95]
	v_mfma_f32_16x16x32_bf16 v[88:91], v[158:161], v[182:185], v[88:91]
	v_mfma_f32_16x16x32_bf16 v[76:79], v[150:153], v[190:193], v[76:79]
	v_mfma_f32_16x16x32_bf16 v[72:75], v[158:161], v[190:193], v[72:75]
	s_barrier
	s_add_i32 s20, s57, s36
	s_mov_b32 m0, s20
	global_load_lds_dwordx4 v130, s[80:81]
	s_add_i32 m0, s20, 0x2000
	s_nop 0
	global_load_lds_dwordx4 v134, s[80:81]
	s_waitcnt vmcnt(10)
	s_barrier
	s_waitcnt lgkmcnt(0)
	s_waitcnt lgkmcnt(0)
	v_mfma_f32_16x16x32_bf16 v[116:119], v[194:197], v[162:165], v[116:119]
	v_mfma_f32_16x16x32_bf16 v[112:115], v[212:215], v[162:165], v[112:115]
	v_mfma_f32_16x16x32_bf16 v[100:103], v[194:197], v[170:173], v[100:103]
	v_mfma_f32_16x16x32_bf16 v[96:99], v[212:215], v[170:173], v[96:99]
	v_mfma_f32_16x16x32_bf16 v[84:87], v[194:197], v[178:181], v[84:87]
	v_mfma_f32_16x16x32_bf16 v[80:83], v[212:215], v[178:181], v[80:83]
	v_mfma_f32_16x16x32_bf16 v[68:71], v[194:197], v[186:189], v[68:71]
	v_mfma_f32_16x16x32_bf16 v[64:67], v[212:215], v[186:189], v[64:67]
	v_mfma_f32_16x16x32_bf16 v[116:119], v[208:211], v[166:169], v[116:119]
	v_mfma_f32_16x16x32_bf16 v[112:115], v[216:219], v[166:169], v[112:115]
	v_mfma_f32_16x16x32_bf16 v[100:103], v[208:211], v[174:177], v[100:103]
	v_mfma_f32_16x16x32_bf16 v[96:99], v[216:219], v[174:177], v[96:99]
	v_mfma_f32_16x16x32_bf16 v[84:87], v[208:211], v[182:185], v[84:87]
	v_mfma_f32_16x16x32_bf16 v[80:83], v[216:219], v[182:185], v[80:83]
	v_mfma_f32_16x16x32_bf16 v[68:71], v[208:211], v[190:193], v[68:71]
	v_mfma_f32_16x16x32_bf16 v[64:67], v[216:219], v[190:193], v[64:67]
	s_mov_b32 m0, s42
	s_barrier
	ds_read_b128 v[162:165], v204 offset:49152
	ds_read_b128 v[166:169], v204 offset:50176
	ds_read_b128 v[170:173], v204 offset:51200
	ds_read_b128 v[174:177], v204 offset:52224
	ds_read_b128 v[178:181], v204 offset:53248
	ds_read_b128 v[182:185], v204 offset:54272
	ds_read_b128 v[186:189], v204 offset:55296
	ds_read_b128 v[190:193], v204 offset:56320
	global_load_lds_dwordx4 v128, s[82:83]
	s_mov_b32 m0, s43
	s_nop 0
	global_load_lds_dwordx4 v132, s[82:83]
	s_barrier
	s_waitcnt lgkmcnt(0)
	s_waitcnt lgkmcnt(0)
	v_mfma_f32_16x16x32_bf16 v[60:63], v[146:149], v[162:165], v[60:63]
	v_mfma_f32_16x16x32_bf16 v[56:59], v[154:157], v[162:165], v[56:59]
	v_mfma_f32_16x16x32_bf16 v[44:47], v[146:149], v[170:173], v[44:47]
	v_mfma_f32_16x16x32_bf16 v[40:43], v[154:157], v[170:173], v[40:43]
	v_mfma_f32_16x16x32_bf16 v[28:31], v[146:149], v[178:181], v[28:31]
	v_mfma_f32_16x16x32_bf16 v[24:27], v[154:157], v[178:181], v[24:27]
	v_mfma_f32_16x16x32_bf16 v[12:15], v[146:149], v[186:189], v[12:15]
	v_mfma_f32_16x16x32_bf16 v[8:11], v[154:157], v[186:189], v[8:11]
	v_mfma_f32_16x16x32_bf16 v[60:63], v[150:153], v[166:169], v[60:63]
	v_mfma_f32_16x16x32_bf16 v[56:59], v[158:161], v[166:169], v[56:59]
	v_mfma_f32_16x16x32_bf16 v[44:47], v[150:153], v[174:177], v[44:47]
	v_mfma_f32_16x16x32_bf16 v[40:43], v[158:161], v[174:177], v[40:43]
	v_mfma_f32_16x16x32_bf16 v[28:31], v[150:153], v[182:185], v[28:31]
	v_mfma_f32_16x16x32_bf16 v[24:27], v[158:161], v[182:185], v[24:27]
	v_mfma_f32_16x16x32_bf16 v[12:15], v[150:153], v[190:193], v[12:15]
	v_mfma_f32_16x16x32_bf16 v[8:11], v[158:161], v[190:193], v[8:11]
	s_barrier
	s_add_u32 s20, s24, 0xb0080
	s_addc_u32 s21, s25, 0
	s_add_i32 s24, s26, s36
	s_mov_b32 m0, s24
	s_nop 0
	global_load_lds_dwordx4 v130, s[20:21]
	s_add_i32 m0, s24, 0x2000
	s_nop 0
	global_load_lds_dwordx4 v134, s[20:21]
	s_waitcnt vmcnt(8)
	s_barrier
	v_mfma_f32_16x16x32_bf16 v[52:55], v[194:197], v[162:165], v[52:55]
	v_mfma_f32_16x16x32_bf16 v[48:51], v[212:215], v[162:165], v[48:51]
	v_mfma_f32_16x16x32_bf16 v[36:39], v[194:197], v[170:173], v[36:39]
	v_mfma_f32_16x16x32_bf16 v[32:35], v[212:215], v[170:173], v[32:35]
	v_mfma_f32_16x16x32_bf16 v[20:23], v[194:197], v[178:181], v[20:23]
	v_mfma_f32_16x16x32_bf16 v[16:19], v[212:215], v[178:181], v[16:19]
	v_mfma_f32_16x16x32_bf16 v[4:7], v[194:197], v[186:189], v[4:7]
	v_mfma_f32_16x16x32_bf16 v[0:3], v[212:215], v[186:189], v[0:3]
	v_mfma_f32_16x16x32_bf16 v[52:55], v[208:211], v[166:169], v[52:55]
	v_mfma_f32_16x16x32_bf16 v[48:51], v[216:219], v[166:169], v[48:51]
	v_mfma_f32_16x16x32_bf16 v[36:39], v[208:211], v[174:177], v[36:39]
	v_mfma_f32_16x16x32_bf16 v[32:35], v[216:219], v[174:177], v[32:35]
	v_mfma_f32_16x16x32_bf16 v[20:23], v[208:211], v[182:185], v[20:23]
	v_mfma_f32_16x16x32_bf16 v[16:19], v[216:219], v[182:185], v[16:19]
	v_mfma_f32_16x16x32_bf16 v[4:7], v[208:211], v[190:193], v[4:7]
	v_mfma_f32_16x16x32_bf16 v[0:3], v[216:219], v[190:193], v[0:3]
	s_add_i32 s56, s56, 2
	s_add_u32 s54, s54, 0x100
	s_addc_u32 s55, s55, 0
	s_cmp_gt_u32 s56, 41
	s_mov_b64 s[20:21], s[22:23]
	s_barrier
	s_cbranch_scc0 .LBB0_973
	s_setprio 0
	s_cmpk_gt_u32 s30, 0xff
	s_cbranch_scc1 .Lg973_nox
	s_barrier
	s_setprio 1
